# S5 scan1: u prefetch 4-deep register ring (4x unroll), counted vmcnt
# baseline (speedup 1.0000x reference)
; #define LDS_WAIT() asm volatile("s_waitcnt lgkmcnt(0)" ::: "memory")
; __device__ __forceinline__ u32x2 s5_load_u(const bf16_t* U, int t0, int g, int lane) { if (t0 > T - 16) t0 = T - 16; return *(const u32x2*)(U + (size_t)(t0 + (lane >> 2)) * D + g * 16 + (lane & 3) * 4); }
; __device__ __forceinline__ void s5_item_setup(const S5Params& P, int g, int lane, LAS unsigned char* wlds, S5Item& L) {
;     ...
;         const float lr = P.a_re[g * 64 + lane], li = P.a_im[g * 64 + lane], dt = expf(P.log_dt[g]);
;         const float mag = expf(lr * dt);
;         L.abr = mag * cosf(li * dt); L.abi = mag * sinf(li * dt);
;         const float n_re = L.abr - 1.0f, n_im = L.abi, den = lr * lr + li * li;
;         zt[lane * 2] = (n_re * lr + n_im * li) / den; zt[lane * 2 + 1] = (n_im * lr - n_re * li) / den;
;     }
;     LDS_WAIT(); __builtin_amdgcn_wave_barrier();
;     const int i0 = ((lane >> 4) & 1) * 8; const bool lo_half = lane >= 32;
; #pragma unroll
;     for (int f = 0; f < 8; ++f) {
;         const int pp = 16 * f + (lane & 15), p = pp >> 1; const bool im = pp & 1;
;         const float zr = zt[p * 2], zi = zt[p * 2 + 1];
;         const f32x4* br = (const f32x4*)(P.b_re + (size_t)(g * 64 + p) * 16 + i0); const f32x4* bi = (const f32x4*)(P.b_im + (size_t)(g * 64 + p) * 16 + i0);
;         float v[8];
; #pragma unroll
;         for (int q = 0; q < 2; ++q) { const f32x4 r = br[q], m = bi[q];
; __device__ __forceinline__ void s5_scan1(LAS unsigned char* lds, const S5Params& P, const bf16_t* U, float* ES, int bid, int G) {
;     ...
;         u32x2 uq0 = s5_load_u(U, c * S5_L, g, lane), uq1 = s5_load_u(U, c * S5_L + 16, g, lane), uq2 = s5_load_u(U, c * S5_L + 32, g, lane), uq3 = s5_load_u(U, c * S5_L + 48, g, lane);
.LBB0_1178:
	s_or_b64 exec, exec, s[8:9]
	s_waitcnt vmcnt(0)
	v_mul_f32_e32 v6, v2, v6
	v_mul_f32_e32 v9, 0x3fb8aa3b, v6
	s_mov_b32 s1, 0x3fb8aa3b
	v_fma_f32 v10, v6, s1, -v9
	v_rndne_f32_e32 v13, v9
	v_fmac_f32_e32 v10, 0x32a5705f, v6
	v_sub_f32_e32 v9, v9, v13
	v_add_f32_e32 v9, v9, v10
	v_exp_f32_e32 v9, v9
	v_cvt_i32_f32_e32 v10, v13
	s_mov_b32 s1, 0xc2ce8ed0
	v_cmp_ngt_f32_e32 vcc, s1, v6
	s_mov_b32 s1, 0x42b17218
	v_ldexp_f32 v9, v9, v10
	v_cndmask_b32_e32 v9, 0, v9, vcc
	v_cmp_nlt_f32_e32 vcc, s1, v6
	s_brev_b32 s1, 1
	s_ashr_i32 s10, s44, 7
	v_cndmask_b32_e32 v6, v241, v9, vcc
	v_mul_f32_e32 v9, v8, v8
	v_fmamk_f32 v10, v9, 0xb94c1982, v182
	v_fmaak_f32 v10, v9, v10, 0xbe2aaa9d
	v_mul_f32_e32 v10, v9, v10
	v_fmac_f32_e32 v8, v8, v10
	v_fmamk_f32 v10, v9, 0x37d75334, v251
	v_fmaak_f32 v10, v9, v10, 0x3d2aabf7
	v_fmaak_f32 v10, v9, v10, 0xbf000004
	v_fma_f32 v9, v9, v10, 1.0
	v_and_b32_e32 v10, 1, v7
	v_cmp_eq_u32_e32 vcc, 0, v10
	v_lshlrev_b32_e32 v7, 30, v7
	v_mov_b32_e32 v10, 0x7fc00000
	v_cndmask_b32_e64 v8, -v8, v9, vcc
	v_bitop3_b32 v7, v7, v8, s1 bitop3:0x6c
	v_mul_f32_e32 v8, v12, v12
	v_fmamk_f32 v9, v8, 0xb94c1982, v182
	v_fmaak_f32 v9, v8, v9, 0xbe2aaa9d
	v_mul_f32_e32 v9, v8, v9
	v_fmac_f32_e32 v12, v12, v9
	v_fmamk_f32 v9, v8, 0x37d75334, v251
	v_fmaak_f32 v9, v8, v9, 0x3d2aabf7
	v_fmaak_f32 v9, v8, v9, 0xbf000004
	v_fma_f32 v8, v8, v9, 1.0
	v_and_b32_e32 v9, 1, v11
	s_movk_i32 s1, 0x1f8
	v_cmp_eq_u32_e64 s[8:9], 0, v9
	v_lshlrev_b32_e32 v9, 30, v11
	v_cmp_class_f32_e64 vcc, v4, s1
	v_and_b32_e32 v9, 0x80000000, v9
	v_xor_b32_e32 v4, v5, v4
	v_cndmask_b32_e64 v8, v8, v12, s[8:9]
	v_xor_b32_e32 v4, v4, v9
	v_xor_b32_e32 v4, v4, v8
	v_cndmask_b32_e32 v7, v10, v7, vcc
	v_cndmask_b32_e32 v4, v10, v4, vcc
	v_mul_f32_e32 v62, v6, v7
	v_mul_f32_e32 v65, v6, v4
	v_fma_f32 v64, v6, v7, -1.0
	v_mov_b32_e32 v6, v3
	v_pk_mul_f32 v[4:5], v[2:3], v[2:3]
	v_pk_mul_f32 v[6:7], v[6:7], v[64:65] op_sel:[0,1] op_sel_hi:[0,0]
	v_pk_fma_f32 v[8:9], v[2:3], v[64:65], v[6:7]
	v_pk_fma_f32 v[2:3], v[2:3], v[64:65], v[6:7] op_sel_hi:[0,1,1] neg_lo:[0,0,1] neg_hi:[0,0,1]
	v_pk_add_f32 v[4:5], v[4:5], v[4:5] op_sel:[0,1] op_sel_hi:[0,1]
	v_div_scale_f32 v2, s[8:9], v5, v5, v3
	v_rcp_f32_e32 v6, v2
	s_lshl_b32 s42, s0, 5
	v_add_u32_e32 v91, s45, v50
	v_mov_b32_e32 v61, v0
	v_fma_f32 v7, -v2, v6, 1.0
	v_fmac_f32_e32 v6, v7, v6
	v_div_scale_f32 v7, vcc, v3, v5, v3
	v_mul_f32_e32 v9, v7, v6
	v_fma_f32 v10, -v2, v9, v7
	v_fmac_f32_e32 v9, v10, v6
	v_fma_f32 v2, -v2, v9, v7
	v_div_fmas_f32 v2, v2, v6, v9
	v_div_fixup_f32 v3, v2, v5, v3
	v_div_scale_f32 v2, s[8:9], v4, v4, v8
	v_rcp_f32_e32 v5, v2
	s_lshl_b32 s8, s10, 8
	s_or_b32 s0, s8, 48
	s_min_i32 s0, s0, 0x1ff0
	v_fma_f32 v6, -v2, v5, 1.0
	v_fmac_f32_e32 v5, v6, v5
	v_div_scale_f32 v6, vcc, v8, v4, v8
	v_mul_f32_e32 v7, v6, v5
	v_fma_f32 v9, -v2, v7, v6
	v_fmac_f32_e32 v7, v9, v5
	v_fma_f32 v2, -v2, v7, v6
	v_div_fmas_f32 v2, v2, v5, v7
	v_div_fixup_f32 v2, v2, v4, v8
	ds_write_b64 v91, v[2:3] offset:13824
	v_or_b32_e32 v2, s0, v87
	v_ashrrev_i32_e32 v3, 31, v2
	v_lshlrev_b64 v[2:3], 12, v[2:3]
	v_lshl_add_u64 v[2:3], s[58:59], 0, v[2:3]
	v_lshl_add_u64 v[2:3], v[2:3], 0, s[42:43]
	s_or_b32 s0, s8, 32
	v_lshl_add_u64 v[2:3], v[2:3], 0, v[60:61]
	s_min_i32 s0, s0, 0x1ff0
	s_waitcnt lgkmcnt(0)
	global_load_dwordx2 v[70:71], v[2:3], off
	v_or_b32_e32 v2, s0, v87
	v_ashrrev_i32_e32 v3, 31, v2
	v_lshlrev_b64 v[2:3], 12, v[2:3]
	v_lshl_add_u64 v[2:3], s[58:59], 0, v[2:3]
	v_lshl_add_u64 v[2:3], v[2:3], 0, s[42:43]
	s_or_b32 s0, s8, 16
	v_lshl_add_u64 v[2:3], v[2:3], 0, v[60:61]
	s_min_i32 s0, s0, 0x1ff0
	global_load_dwordx2 v[68:69], v[2:3], off
	v_or_b32_e32 v2, s0, v87
	v_ashrrev_i32_e32 v3, 31, v2
	v_lshlrev_b64 v[2:3], 12, v[2:3]
	v_lshl_add_u64 v[2:3], s[58:59], 0, v[2:3]
	v_lshl_add_u64 v[2:3], v[2:3], 0, s[42:43]
	v_lshl_add_u64 v[2:3], v[2:3], 0, v[60:61]
	global_load_dwordx2 v[72:73], v[2:3], off
	v_or_b32_e32 v2, s8, v87
	v_ashrrev_i32_e32 v3, 31, v2
	v_lshlrev_b64 v[2:3], 12, v[2:3]
	v_lshl_add_u64 v[2:3], s[58:59], 0, v[2:3]
	v_lshl_add_u64 v[2:3], v[2:3], 0, s[42:43]
	v_lshl_add_u64 v[2:3], v[2:3], 0, v[60:61]
	global_load_dwordx2 v[76:77], v[2:3], off
	v_or_b32_e32 v2, s68, v86
	v_lshlrev_b32_e32 v2, 6, v2
	v_mov_b32_e32 v3, v0
	v_add_u32_e32 v30, 0x3000, v79
	v_lshl_add_u64 v[8:9], v[56:57], 0, v[2:3]
	v_lshl_add_u64 v[2:3], v[58:59], 0, v[2:3]
	ds_read2_b64 v[10:13], v30 offset0:240 offset1:248
	global_load_dwordx4 v[4:7], v[8:9], off offset:16
	global_load_dwordx4 v[14:17], v[8:9], off
	global_load_dwordx4 v[18:21], v[2:3], off offset:16
	global_load_dwordx4 v[22:25], v[2:3], off
	v_mov_b32_e32 v74, 0
	v_lshl_add_u64 v[66:67], v[52:53], 0, s[42:43]
	s_or_b32 s0, s8, 0xf0
	v_mov_b32_e32 v63, v62
	v_mov_b32_e32 v64, v65
	v_mov_b32_e32 v75, v74
	s_waitcnt vmcnt(0) lgkmcnt(0)
; __device__ __forceinline__ void s5_item_setup(const S5Params& P, int g, int lane, LAS unsigned char* wlds, S5Item& L) {
;     ...
;     for (int f = 0; f < 8; ++f) {
;         const int pp = 16 * f + (lane & 15), p = pp >> 1; const bool im = pp & 1;
;         const float zr = zt[p * 2], zi = zt[p * 2 + 1];
;         const f32x4* br = (const f32x4*)(P.b_re + (size_t)(g * 64 + p) * 16 + i0); const f32x4* bi = (const f32x4*)(P.b_im + (size_t)(g * 64 + p) * 16 + i0);
;         float v[8];
; #pragma unroll
;         for (int q = 0; q < 2; ++q) { const f32x4 r = br[q], m = bi[q];
; #pragma unroll
;             for (int j = 0; j < 4; ++j) v[q * 4 + j] = im ? (zr * m[j] + zi * r[j]) : (zr * r[j] - zi * m[j]); }
;         u32x4 w;
; #pragma unroll
;         for (int q = 0; q < 4; ++q) { const unsigned h2 = cvt_pk_bf16(v[2 * q], v[2 * q + 1]);
;             const float r0 = v[2 * q] - bflo(h2), r1 = v[2 * q + 1] - bfhi(h2); w[q] = lo_half ? cvt_pk_bf16(r0, r1) : h2; }
;         L.bf[f] = __builtin_bit_cast(bf16x8, w);
;     }
	v_pk_mul_f32 v[2:3], v[12:13], v[22:23] op_sel:[1,0]
	v_pk_mul_f32 v[8:9], v[12:13], v[22:23] op_sel_hi:[0,1]
	v_pk_fma_f32 v[2:3], v[12:13], v[14:15], v[2:3] op_sel_hi:[0,1,1] neg_lo:[0,0,1] neg_hi:[0,0,1]
	v_pk_fma_f32 v[8:9], v[12:13], v[14:15], v[8:9] op_sel:[1,0,0]
	s_nop 0
	v_cndmask_b32_e64 v3, v9, v3, s[6:7]
	v_cndmask_b32_e64 v2, v8, v2, s[6:7]
	v_cvt_pk_bf16_f32 v14, v2, v3
	v_lshlrev_b32_e32 v8, 16, v14
	v_and_b32_e32 v9, 0xffff0000, v14
	v_pk_add_f32 v[2:3], v[2:3], v[8:9] neg_lo:[0,1] neg_hi:[0,1]
	v_pk_mul_f32 v[8:9], v[12:13], v[24:25] op_sel:[1,0]
	v_cvt_pk_bf16_f32 v2, v2, v3
	v_cndmask_b32_e64 v2, v14, v2, s[4:5]
	v_pk_mul_f32 v[14:15], v[12:13], v[24:25] op_sel_hi:[0,1]
	v_pk_fma_f32 v[8:9], v[12:13], v[16:17], v[8:9] op_sel_hi:[0,1,1] neg_lo:[0,0,1] neg_hi:[0,0,1]
	v_pk_fma_f32 v[14:15], v[12:13], v[16:17], v[14:15] op_sel:[1,0,0]
	v_mov_b32_e32 v17, v0
	v_cndmask_b32_e64 v9, v15, v9, s[6:7]
	v_cndmask_b32_e64 v8, v14, v8, s[6:7]
	v_cvt_pk_bf16_f32 v3, v8, v9
	v_lshlrev_b32_e32 v14, 16, v3
	v_and_b32_e32 v15, 0xffff0000, v3
	v_pk_add_f32 v[8:9], v[8:9], v[14:15] neg_lo:[0,1] neg_hi:[0,1]
	v_pk_mul_f32 v[14:15], v[12:13], v[18:19] op_sel_hi:[0,1]
	v_cvt_pk_bf16_f32 v8, v8, v9
	v_cndmask_b32_e64 v3, v3, v8, s[4:5]
	v_pk_mul_f32 v[8:9], v[12:13], v[18:19] op_sel:[1,0]
	s_nop 0
	v_pk_fma_f32 v[8:9], v[12:13], v[4:5], v[8:9] op_sel_hi:[0,1,1] neg_lo:[0,0,1] neg_hi:[0,0,1]
	v_pk_fma_f32 v[4:5], v[12:13], v[4:5], v[14:15] op_sel:[1,0,0]
	s_nop 0
	v_cndmask_b32_e64 v5, v5, v9, s[6:7]
	v_cndmask_b32_e64 v4, v4, v8, s[6:7]
	v_cvt_pk_bf16_f32 v14, v4, v5
	v_lshlrev_b32_e32 v8, 16, v14
	v_and_b32_e32 v9, 0xffff0000, v14
	v_pk_add_f32 v[4:5], v[4:5], v[8:9] neg_lo:[0,1] neg_hi:[0,1]
	v_pk_mul_f32 v[8:9], v[12:13], v[20:21] op_sel:[1,0]
	v_cvt_pk_bf16_f32 v4, v4, v5
	v_cndmask_b32_e64 v4, v14, v4, s[4:5]
	v_pk_mul_f32 v[14:15], v[12:13], v[20:21] op_sel_hi:[0,1]
	v_pk_fma_f32 v[8:9], v[12:13], v[6:7], v[8:9] op_sel_hi:[0,1,1] neg_lo:[0,0,1] neg_hi:[0,0,1]
	v_pk_fma_f32 v[6:7], v[12:13], v[6:7], v[14:15] op_sel:[1,0,0]
	s_nop 0
	v_cndmask_b32_e64 v7, v7, v9, s[6:7]
	v_cndmask_b32_e64 v6, v6, v8, s[6:7]
	v_cvt_pk_bf16_f32 v5, v6, v7
	v_lshlrev_b32_e32 v8, 16, v5
	v_and_b32_e32 v9, 0xffff0000, v5
	v_pk_add_f32 v[6:7], v[6:7], v[8:9] neg_lo:[0,1] neg_hi:[0,1]
	s_nop 0
	v_cvt_pk_bf16_f32 v6, v6, v7
	v_cndmask_b32_e64 v5, v5, v6, s[4:5]
	v_or_b32_e32 v6, s68, v85
	v_lshlrev_b32_e32 v16, 6, v6
	v_lshl_add_u64 v[6:7], v[56:57], 0, v[16:17]
	v_lshl_add_u64 v[20:21], v[58:59], 0, v[16:17]
	global_load_dwordx4 v[12:15], v[6:7], off offset:16
	s_nop 0
	global_load_dwordx4 v[6:9], v[6:7], off
	s_nop 0
	global_load_dwordx4 v[16:19], v[20:21], off offset:16
	s_nop 0
	global_load_dwordx4 v[20:23], v[20:21], off
	s_waitcnt vmcnt(0)
	v_pk_mul_f32 v[24:25], v[10:11], v[20:21] op_sel:[1,0]
	v_pk_mul_f32 v[20:21], v[10:11], v[20:21] op_sel_hi:[0,1]
	v_pk_fma_f32 v[24:25], v[10:11], v[6:7], v[24:25] op_sel_hi:[0,1,1] neg_lo:[0,0,1] neg_hi:[0,0,1]
	v_pk_fma_f32 v[6:7], v[10:11], v[6:7], v[20:21] op_sel:[1,0,0]
	s_nop 0
	v_cndmask_b32_e64 v7, v7, v25, s[6:7]
	v_cndmask_b32_e64 v6, v6, v24, s[6:7]
	v_cvt_pk_bf16_f32 v24, v6, v7
	v_lshlrev_b32_e32 v20, 16, v24
	v_and_b32_e32 v21, 0xffff0000, v24
	v_pk_add_f32 v[6:7], v[6:7], v[20:21] neg_lo:[0,1] neg_hi:[0,1]
	v_pk_mul_f32 v[20:21], v[10:11], v[22:23] op_sel:[1,0]
	v_pk_mul_f32 v[22:23], v[10:11], v[22:23] op_sel_hi:[0,1]
	v_pk_fma_f32 v[20:21], v[10:11], v[8:9], v[20:21] op_sel_hi:[0,1,1] neg_lo:[0,0,1] neg_hi:[0,0,1]
	v_pk_fma_f32 v[8:9], v[10:11], v[8:9], v[22:23] op_sel:[1,0,0]
	v_cvt_pk_bf16_f32 v6, v6, v7
	v_cndmask_b32_e64 v9, v9, v21, s[6:7]
	v_cndmask_b32_e64 v8, v8, v20, s[6:7]
	v_cvt_pk_bf16_f32 v7, v8, v9
	v_lshlrev_b32_e32 v20, 16, v7
	v_and_b32_e32 v21, 0xffff0000, v7
	v_pk_add_f32 v[8:9], v[8:9], v[20:21] neg_lo:[0,1] neg_hi:[0,1]
	v_cndmask_b32_e64 v6, v24, v6, s[4:5]
	v_cvt_pk_bf16_f32 v8, v8, v9
	v_cndmask_b32_e64 v7, v7, v8, s[4:5]
	v_pk_mul_f32 v[8:9], v[10:11], v[16:17] op_sel:[1,0]
	v_pk_mul_f32 v[16:17], v[10:11], v[16:17] op_sel_hi:[0,1]
	v_pk_fma_f32 v[8:9], v[10:11], v[12:13], v[8:9] op_sel_hi:[0,1,1] neg_lo:[0,0,1] neg_hi:[0,0,1]
	v_pk_fma_f32 v[12:13], v[10:11], v[12:13], v[16:17] op_sel:[1,0,0]
	s_nop 0
	v_cndmask_b32_e64 v9, v13, v9, s[6:7]
	v_cndmask_b32_e64 v8, v12, v8, s[6:7]
	v_cvt_pk_bf16_f32 v16, v8, v9
	v_lshlrev_b32_e32 v12, 16, v16
	v_and_b32_e32 v13, 0xffff0000, v16
	v_pk_add_f32 v[8:9], v[8:9], v[12:13] neg_lo:[0,1] neg_hi:[0,1]
	v_pk_mul_f32 v[12:13], v[10:11], v[18:19] op_sel:[1,0]
	v_cvt_pk_bf16_f32 v8, v8, v9
	v_cndmask_b32_e64 v8, v16, v8, s[4:5]
	v_pk_mul_f32 v[16:17], v[10:11], v[18:19] op_sel_hi:[0,1]
	v_pk_fma_f32 v[12:13], v[10:11], v[14:15], v[12:13] op_sel_hi:[0,1,1] neg_lo:[0,0,1] neg_hi:[0,0,1]
	v_pk_fma_f32 v[10:11], v[10:11], v[14:15], v[16:17] op_sel:[1,0,0]
	ds_read2_b64 v[18:21], v30 offset0:224 offset1:232
	v_cndmask_b32_e64 v11, v11, v13, s[6:7]
	v_cndmask_b32_e64 v10, v10, v12, s[6:7]
	v_cvt_pk_bf16_f32 v9, v10, v11
	v_lshlrev_b32_e32 v12, 16, v9
	v_and_b32_e32 v13, 0xffff0000, v9
	v_pk_add_f32 v[10:11], v[10:11], v[12:13] neg_lo:[0,1] neg_hi:[0,1]
	s_nop 0
	v_cvt_pk_bf16_f32 v10, v10, v11
	v_cndmask_b32_e64 v9, v9, v10, s[4:5]
	v_or_b32_e32 v10, s68, v84
	v_lshlrev_b32_e32 v10, 6, v10
	v_mov_b32_e32 v11, v0
	v_lshl_add_u64 v[16:17], v[56:57], 0, v[10:11]
	v_lshl_add_u64 v[10:11], v[58:59], 0, v[10:11]
	global_load_dwordx4 v[12:15], v[16:17], off offset:16
	global_load_dwordx4 v[22:25], v[16:17], off
	global_load_dwordx4 v[26:29], v[10:11], off offset:16
	global_load_dwordx4 v[32:35], v[10:11], off
	s_waitcnt vmcnt(0) lgkmcnt(0)
; __device__ __forceinline__ void s5_item_setup(const S5Params& P, int g, int lane, LAS unsigned char* wlds, S5Item& L) {
;     ...
;     for (int f = 0; f < 8; ++f) {
;         const int pp = 16 * f + (lane & 15), p = pp >> 1; const bool im = pp & 1;
;         const float zr = zt[p * 2], zi = zt[p * 2 + 1];
;         const f32x4* br = (const f32x4*)(P.b_re + (size_t)(g * 64 + p) * 16 + i0); const f32x4* bi = (const f32x4*)(P.b_im + (size_t)(g * 64 + p) * 16 + i0);
;         float v[8];
; #pragma unroll
;         for (int q = 0; q < 2; ++q) { const f32x4 r = br[q], m = bi[q];
; #pragma unroll
;             for (int j = 0; j < 4; ++j) v[q * 4 + j] = im ? (zr * m[j] + zi * r[j]) : (zr * r[j] - zi * m[j]); }
;         u32x4 w;
; #pragma unroll
;         for (int q = 0; q < 4; ++q) { const unsigned h2 = cvt_pk_bf16(v[2 * q], v[2 * q + 1]);
;             const float r0 = v[2 * q] - bflo(h2), r1 = v[2 * q + 1] - bfhi(h2); w[q] = lo_half ? cvt_pk_bf16(r0, r1) : h2; }
;         L.bf[f] = __builtin_bit_cast(bf16x8, w);
;     }
	v_pk_mul_f32 v[10:11], v[20:21], v[32:33] op_sel:[1,0]
	v_pk_mul_f32 v[16:17], v[20:21], v[32:33] op_sel_hi:[0,1]
	v_pk_fma_f32 v[10:11], v[20:21], v[22:23], v[10:11] op_sel_hi:[0,1,1] neg_lo:[0,0,1] neg_hi:[0,0,1]
	v_pk_fma_f32 v[16:17], v[20:21], v[22:23], v[16:17] op_sel:[1,0,0]
	s_nop 0
	v_cndmask_b32_e64 v11, v17, v11, s[6:7]
	v_cndmask_b32_e64 v10, v16, v10, s[6:7]
	v_cvt_pk_bf16_f32 v22, v10, v11
	v_lshlrev_b32_e32 v16, 16, v22
	v_and_b32_e32 v17, 0xffff0000, v22
	v_pk_add_f32 v[10:11], v[10:11], v[16:17] neg_lo:[0,1] neg_hi:[0,1]
	v_pk_mul_f32 v[16:17], v[20:21], v[34:35] op_sel:[1,0]
	v_cvt_pk_bf16_f32 v10, v10, v11
	v_cndmask_b32_e64 v10, v22, v10, s[4:5]
	v_pk_mul_f32 v[22:23], v[20:21], v[34:35] op_sel_hi:[0,1]
	v_pk_fma_f32 v[16:17], v[20:21], v[24:25], v[16:17] op_sel_hi:[0,1,1] neg_lo:[0,0,1] neg_hi:[0,0,1]
	v_pk_fma_f32 v[22:23], v[20:21], v[24:25], v[22:23] op_sel:[1,0,0]
	v_mov_b32_e32 v25, v0
	v_cndmask_b32_e64 v17, v23, v17, s[6:7]
	v_cndmask_b32_e64 v16, v22, v16, s[6:7]
	v_cvt_pk_bf16_f32 v11, v16, v17
	v_lshlrev_b32_e32 v22, 16, v11
	v_and_b32_e32 v23, 0xffff0000, v11
	v_pk_add_f32 v[16:17], v[16:17], v[22:23] neg_lo:[0,1] neg_hi:[0,1]
	v_pk_mul_f32 v[22:23], v[20:21], v[26:27] op_sel_hi:[0,1]
	v_cvt_pk_bf16_f32 v16, v16, v17
	v_cndmask_b32_e64 v11, v11, v16, s[4:5]
	v_pk_mul_f32 v[16:17], v[20:21], v[26:27] op_sel:[1,0]
	s_nop 0
	v_pk_fma_f32 v[16:17], v[20:21], v[12:13], v[16:17] op_sel_hi:[0,1,1] neg_lo:[0,0,1] neg_hi:[0,0,1]
	v_pk_fma_f32 v[12:13], v[20:21], v[12:13], v[22:23] op_sel:[1,0,0]
	s_nop 0
	v_cndmask_b32_e64 v13, v13, v17, s[6:7]
	v_cndmask_b32_e64 v12, v12, v16, s[6:7]
	v_cvt_pk_bf16_f32 v22, v12, v13
	v_lshlrev_b32_e32 v16, 16, v22
	v_and_b32_e32 v17, 0xffff0000, v22
	v_pk_add_f32 v[12:13], v[12:13], v[16:17] neg_lo:[0,1] neg_hi:[0,1]
	v_pk_mul_f32 v[16:17], v[20:21], v[28:29] op_sel:[1,0]
	v_cvt_pk_bf16_f32 v12, v12, v13
	v_cndmask_b32_e64 v12, v22, v12, s[4:5]
	v_pk_mul_f32 v[22:23], v[20:21], v[28:29] op_sel_hi:[0,1]
	v_pk_fma_f32 v[16:17], v[20:21], v[14:15], v[16:17] op_sel_hi:[0,1,1] neg_lo:[0,0,1] neg_hi:[0,0,1]
	v_pk_fma_f32 v[14:15], v[20:21], v[14:15], v[22:23] op_sel:[1,0,0]
	s_nop 0
	v_cndmask_b32_e64 v15, v15, v17, s[6:7]
	v_cndmask_b32_e64 v14, v14, v16, s[6:7]
	v_cvt_pk_bf16_f32 v13, v14, v15
	v_lshlrev_b32_e32 v16, 16, v13
	v_and_b32_e32 v17, 0xffff0000, v13
	v_pk_add_f32 v[14:15], v[14:15], v[16:17] neg_lo:[0,1] neg_hi:[0,1]
	s_nop 0
	v_cvt_pk_bf16_f32 v14, v14, v15
	v_cndmask_b32_e64 v13, v13, v14, s[4:5]
	v_or_b32_e32 v14, s68, v83
	v_lshlrev_b32_e32 v24, 6, v14
	v_lshl_add_u64 v[14:15], v[56:57], 0, v[24:25]
	v_lshl_add_u64 v[28:29], v[58:59], 0, v[24:25]
	global_load_dwordx4 v[20:23], v[14:15], off offset:16
	s_nop 0
	global_load_dwordx4 v[14:17], v[14:15], off
	s_nop 0
	global_load_dwordx4 v[24:27], v[28:29], off offset:16
	global_load_dwordx4 v[32:35], v[28:29], off
	s_waitcnt vmcnt(0)
	v_pk_mul_f32 v[28:29], v[18:19], v[32:33] op_sel:[1,0]
	v_pk_mul_f32 v[32:33], v[18:19], v[32:33] op_sel_hi:[0,1]
	v_pk_fma_f32 v[28:29], v[18:19], v[14:15], v[28:29] op_sel_hi:[0,1,1] neg_lo:[0,0,1] neg_hi:[0,0,1]
	v_pk_fma_f32 v[14:15], v[18:19], v[14:15], v[32:33] op_sel:[1,0,0]
	v_pk_mul_f32 v[32:33], v[18:19], v[34:35] op_sel_hi:[0,1]
	v_cndmask_b32_e64 v15, v15, v29, s[6:7]
	v_cndmask_b32_e64 v14, v14, v28, s[6:7]
	v_cvt_pk_bf16_f32 v31, v14, v15
	v_lshlrev_b32_e32 v28, 16, v31
	v_and_b32_e32 v29, 0xffff0000, v31
	v_pk_add_f32 v[14:15], v[14:15], v[28:29] neg_lo:[0,1] neg_hi:[0,1]
	v_pk_mul_f32 v[28:29], v[18:19], v[34:35] op_sel:[1,0]
	v_cvt_pk_bf16_f32 v14, v14, v15
	v_pk_fma_f32 v[28:29], v[18:19], v[16:17], v[28:29] op_sel_hi:[0,1,1] neg_lo:[0,0,1] neg_hi:[0,0,1]
	v_pk_fma_f32 v[16:17], v[18:19], v[16:17], v[32:33] op_sel:[1,0,0]
	v_cndmask_b32_e64 v14, v31, v14, s[4:5]
	v_cndmask_b32_e64 v17, v17, v29, s[6:7]
	v_cndmask_b32_e64 v16, v16, v28, s[6:7]
	v_cvt_pk_bf16_f32 v15, v16, v17
	v_lshlrev_b32_e32 v28, 16, v15
	v_and_b32_e32 v29, 0xffff0000, v15
	v_pk_add_f32 v[16:17], v[16:17], v[28:29] neg_lo:[0,1] neg_hi:[0,1]
	s_nop 0
	v_cvt_pk_bf16_f32 v16, v16, v17
	v_cndmask_b32_e64 v15, v15, v16, s[4:5]
	v_pk_mul_f32 v[16:17], v[18:19], v[24:25] op_sel:[1,0]
	v_pk_mul_f32 v[24:25], v[18:19], v[24:25] op_sel_hi:[0,1]
	v_pk_fma_f32 v[16:17], v[18:19], v[20:21], v[16:17] op_sel_hi:[0,1,1] neg_lo:[0,0,1] neg_hi:[0,0,1]
	v_pk_fma_f32 v[20:21], v[18:19], v[20:21], v[24:25] op_sel:[1,0,0]
	s_nop 0
	v_cndmask_b32_e64 v17, v21, v17, s[6:7]
	v_cndmask_b32_e64 v16, v20, v16, s[6:7]
	v_cvt_pk_bf16_f32 v24, v16, v17
	v_lshlrev_b32_e32 v20, 16, v24
	v_and_b32_e32 v21, 0xffff0000, v24
	v_pk_add_f32 v[16:17], v[16:17], v[20:21] neg_lo:[0,1] neg_hi:[0,1]
	v_pk_mul_f32 v[20:21], v[18:19], v[26:27] op_sel:[1,0]
	v_cvt_pk_bf16_f32 v16, v16, v17
	v_cndmask_b32_e64 v16, v24, v16, s[4:5]
	v_pk_mul_f32 v[24:25], v[18:19], v[26:27] op_sel_hi:[0,1]
	v_pk_fma_f32 v[20:21], v[18:19], v[22:23], v[20:21] op_sel_hi:[0,1,1] neg_lo:[0,0,1] neg_hi:[0,0,1]
	v_pk_fma_f32 v[18:19], v[18:19], v[22:23], v[24:25] op_sel:[1,0,0]
	ds_read2_b64 v[26:29], v30 offset0:208 offset1:216
	v_cndmask_b32_e64 v19, v19, v21, s[6:7]
	v_cndmask_b32_e64 v18, v18, v20, s[6:7]
	v_cvt_pk_bf16_f32 v17, v18, v19
	v_lshlrev_b32_e32 v20, 16, v17
	v_and_b32_e32 v21, 0xffff0000, v17
	v_pk_add_f32 v[18:19], v[18:19], v[20:21] neg_lo:[0,1] neg_hi:[0,1]
	s_nop 0
	v_cvt_pk_bf16_f32 v18, v18, v19
	v_cndmask_b32_e64 v17, v17, v18, s[4:5]
	v_or_b32_e32 v18, s68, v82
	v_lshlrev_b32_e32 v18, 6, v18
	v_mov_b32_e32 v19, v0
	v_lshl_add_u64 v[24:25], v[56:57], 0, v[18:19]
	v_lshl_add_u64 v[18:19], v[58:59], 0, v[18:19]
	global_load_dwordx4 v[20:23], v[24:25], off offset:16
	global_load_dwordx4 v[32:35], v[24:25], off
	global_load_dwordx4 v[36:39], v[18:19], off offset:16
	global_load_dwordx4 v[40:43], v[18:19], off
	s_waitcnt vmcnt(0) lgkmcnt(0)
; __device__ __forceinline__ void s5_item_setup(const S5Params& P, int g, int lane, LAS unsigned char* wlds, S5Item& L) {
;     ...
;     for (int f = 0; f < 8; ++f) {
;         const int pp = 16 * f + (lane & 15), p = pp >> 1; const bool im = pp & 1;
;         const float zr = zt[p * 2], zi = zt[p * 2 + 1];
;         const f32x4* br = (const f32x4*)(P.b_re + (size_t)(g * 64 + p) * 16 + i0); const f32x4* bi = (const f32x4*)(P.b_im + (size_t)(g * 64 + p) * 16 + i0);
;         float v[8];
; #pragma unroll
;         for (int q = 0; q < 2; ++q) { const f32x4 r = br[q], m = bi[q];
; #pragma unroll
;             for (int j = 0; j < 4; ++j) v[q * 4 + j] = im ? (zr * m[j] + zi * r[j]) : (zr * r[j] - zi * m[j]); }
;         u32x4 w;
; #pragma unroll
;         for (int q = 0; q < 4; ++q) { const unsigned h2 = cvt_pk_bf16(v[2 * q], v[2 * q + 1]);
;             const float r0 = v[2 * q] - bflo(h2), r1 = v[2 * q + 1] - bfhi(h2); w[q] = lo_half ? cvt_pk_bf16(r0, r1) : h2; }
;         L.bf[f] = __builtin_bit_cast(bf16x8, w);
;     }
	v_pk_mul_f32 v[18:19], v[28:29], v[40:41] op_sel:[1,0]
	v_pk_mul_f32 v[24:25], v[28:29], v[40:41] op_sel_hi:[0,1]
	v_pk_fma_f32 v[18:19], v[28:29], v[32:33], v[18:19] op_sel_hi:[0,1,1] neg_lo:[0,0,1] neg_hi:[0,0,1]
	v_pk_fma_f32 v[24:25], v[28:29], v[32:33], v[24:25] op_sel:[1,0,0]
	v_pk_mul_f32 v[32:33], v[28:29], v[42:43] op_sel_hi:[0,1]
	v_cndmask_b32_e64 v19, v25, v19, s[6:7]
	v_cndmask_b32_e64 v18, v24, v18, s[6:7]
	v_cvt_pk_bf16_f32 v31, v18, v19
	v_lshlrev_b32_e32 v24, 16, v31
	v_and_b32_e32 v25, 0xffff0000, v31
	v_pk_add_f32 v[18:19], v[18:19], v[24:25] neg_lo:[0,1] neg_hi:[0,1]
	v_pk_mul_f32 v[24:25], v[28:29], v[42:43] op_sel:[1,0]
	v_pk_fma_f32 v[32:33], v[28:29], v[34:35], v[32:33] op_sel:[1,0,0]
	v_pk_fma_f32 v[24:25], v[28:29], v[34:35], v[24:25] op_sel_hi:[0,1,1] neg_lo:[0,0,1] neg_hi:[0,0,1]
	v_cndmask_b32_e64 v25, v33, v25, s[6:7]
	v_cndmask_b32_e64 v24, v32, v24, s[6:7]
	v_cvt_pk_bf16_f32 v18, v18, v19
	v_cvt_pk_bf16_f32 v19, v24, v25
	v_lshlrev_b32_e32 v32, 16, v19
	v_and_b32_e32 v33, 0xffff0000, v19
	v_pk_add_f32 v[24:25], v[24:25], v[32:33] neg_lo:[0,1] neg_hi:[0,1]
	v_pk_mul_f32 v[32:33], v[28:29], v[36:37] op_sel_hi:[0,1]
	v_cvt_pk_bf16_f32 v24, v24, v25
	v_cndmask_b32_e64 v19, v19, v24, s[4:5]
	v_pk_mul_f32 v[24:25], v[28:29], v[36:37] op_sel:[1,0]
	v_cndmask_b32_e64 v18, v31, v18, s[4:5]
	v_pk_fma_f32 v[24:25], v[28:29], v[20:21], v[24:25] op_sel_hi:[0,1,1] neg_lo:[0,0,1] neg_hi:[0,0,1]
	v_pk_fma_f32 v[20:21], v[28:29], v[20:21], v[32:33] op_sel:[1,0,0]
	v_pk_mul_f32 v[32:33], v[28:29], v[38:39] op_sel_hi:[0,1]
	v_cndmask_b32_e64 v21, v21, v25, s[6:7]
	v_cndmask_b32_e64 v20, v20, v24, s[6:7]
	v_cvt_pk_bf16_f32 v31, v20, v21
	v_lshlrev_b32_e32 v24, 16, v31
	v_and_b32_e32 v25, 0xffff0000, v31
	v_pk_add_f32 v[20:21], v[20:21], v[24:25] neg_lo:[0,1] neg_hi:[0,1]
	v_pk_mul_f32 v[24:25], v[28:29], v[38:39] op_sel:[1,0]
	v_cvt_pk_bf16_f32 v20, v20, v21
	v_pk_fma_f32 v[24:25], v[28:29], v[22:23], v[24:25] op_sel_hi:[0,1,1] neg_lo:[0,0,1] neg_hi:[0,0,1]
	v_pk_fma_f32 v[22:23], v[28:29], v[22:23], v[32:33] op_sel:[1,0,0]
	v_mov_b32_e32 v29, v0
	v_cndmask_b32_e64 v23, v23, v25, s[6:7]
	v_cndmask_b32_e64 v22, v22, v24, s[6:7]
	v_cvt_pk_bf16_f32 v21, v22, v23
	v_lshlrev_b32_e32 v24, 16, v21
	v_and_b32_e32 v25, 0xffff0000, v21
	v_pk_add_f32 v[22:23], v[22:23], v[24:25] neg_lo:[0,1] neg_hi:[0,1]
	v_cndmask_b32_e64 v20, v31, v20, s[4:5]
	v_cvt_pk_bf16_f32 v22, v22, v23
	v_cndmask_b32_e64 v21, v21, v22, s[4:5]
	v_or_b32_e32 v22, s68, v81
	v_lshlrev_b32_e32 v28, 6, v22
	v_lshl_add_u64 v[22:23], v[56:57], 0, v[28:29]
	v_lshl_add_u64 v[28:29], v[58:59], 0, v[28:29]
	global_load_dwordx4 v[32:35], v[22:23], off offset:16
	s_nop 0
	global_load_dwordx4 v[22:25], v[22:23], off
	s_nop 0
	global_load_dwordx4 v[36:39], v[28:29], off offset:16
	global_load_dwordx4 v[40:43], v[28:29], off
	s_waitcnt vmcnt(0)
	v_pk_mul_f32 v[28:29], v[26:27], v[40:41] op_sel:[1,0]
	v_pk_mul_f32 v[40:41], v[26:27], v[40:41] op_sel_hi:[0,1]
	v_pk_fma_f32 v[28:29], v[26:27], v[22:23], v[28:29] op_sel_hi:[0,1,1] neg_lo:[0,0,1] neg_hi:[0,0,1]
	v_pk_fma_f32 v[22:23], v[26:27], v[22:23], v[40:41] op_sel:[1,0,0]
	v_pk_mul_f32 v[40:41], v[26:27], v[42:43] op_sel_hi:[0,1]
	v_cndmask_b32_e64 v23, v23, v29, s[6:7]
	v_cndmask_b32_e64 v22, v22, v28, s[6:7]
	v_cvt_pk_bf16_f32 v31, v22, v23
	v_lshlrev_b32_e32 v28, 16, v31
	v_and_b32_e32 v29, 0xffff0000, v31
	v_pk_add_f32 v[22:23], v[22:23], v[28:29] neg_lo:[0,1] neg_hi:[0,1]
	v_pk_mul_f32 v[28:29], v[26:27], v[42:43] op_sel:[1,0]
	v_cvt_pk_bf16_f32 v22, v22, v23
	v_pk_fma_f32 v[28:29], v[26:27], v[24:25], v[28:29] op_sel_hi:[0,1,1] neg_lo:[0,0,1] neg_hi:[0,0,1]
	v_pk_fma_f32 v[24:25], v[26:27], v[24:25], v[40:41] op_sel:[1,0,0]
	v_cndmask_b32_e64 v22, v31, v22, s[4:5]
	v_cndmask_b32_e64 v25, v25, v29, s[6:7]
	v_cndmask_b32_e64 v24, v24, v28, s[6:7]
	v_cvt_pk_bf16_f32 v23, v24, v25
	v_lshlrev_b32_e32 v28, 16, v23
	v_and_b32_e32 v29, 0xffff0000, v23
	v_pk_add_f32 v[24:25], v[24:25], v[28:29] neg_lo:[0,1] neg_hi:[0,1]
	v_pk_mul_f32 v[28:29], v[26:27], v[36:37] op_sel_hi:[0,1]
	v_cvt_pk_bf16_f32 v24, v24, v25
	v_cndmask_b32_e64 v23, v23, v24, s[4:5]
	v_pk_mul_f32 v[24:25], v[26:27], v[36:37] op_sel:[1,0]
	v_pk_fma_f32 v[28:29], v[26:27], v[32:33], v[28:29] op_sel:[1,0,0]
	v_pk_fma_f32 v[24:25], v[26:27], v[32:33], v[24:25] op_sel_hi:[0,1,1] neg_lo:[0,0,1] neg_hi:[0,0,1]
	v_cndmask_b32_e64 v25, v29, v25, s[6:7]
	v_cndmask_b32_e64 v24, v28, v24, s[6:7]
	v_cvt_pk_bf16_f32 v31, v24, v25
	v_lshlrev_b32_e32 v28, 16, v31
	v_and_b32_e32 v29, 0xffff0000, v31
	v_pk_add_f32 v[24:25], v[24:25], v[28:29] neg_lo:[0,1] neg_hi:[0,1]
	v_pk_mul_f32 v[28:29], v[26:27], v[38:39] op_sel:[1,0]
	v_pk_mul_f32 v[32:33], v[26:27], v[38:39] op_sel_hi:[0,1]
	v_pk_fma_f32 v[28:29], v[26:27], v[34:35], v[28:29] op_sel_hi:[0,1,1] neg_lo:[0,0,1] neg_hi:[0,0,1]
	v_pk_fma_f32 v[26:27], v[26:27], v[34:35], v[32:33] op_sel:[1,0,0]
	v_cvt_pk_bf16_f32 v24, v24, v25
	v_cndmask_b32_e64 v27, v27, v29, s[6:7]
	v_cndmask_b32_e64 v26, v26, v28, s[6:7]
	v_cvt_pk_bf16_f32 v25, v26, v27
	v_lshlrev_b32_e32 v28, 16, v25
	v_and_b32_e32 v29, 0xffff0000, v25
	v_pk_add_f32 v[26:27], v[26:27], v[28:29] neg_lo:[0,1] neg_hi:[0,1]
	v_mov_b32_e32 v39, v0
	v_cvt_pk_bf16_f32 v26, v26, v27
	v_cndmask_b32_e64 v25, v25, v26, s[4:5]
	v_or_b32_e32 v26, s68, v80
	v_lshlrev_b32_e32 v38, 6, v26
	v_lshl_add_u64 v[26:27], v[56:57], 0, v[38:39]
	v_lshl_add_u64 v[42:43], v[58:59], 0, v[38:39]
	v_cndmask_b32_e64 v24, v31, v24, s[4:5]
	ds_read2_b64 v[30:33], v30 offset0:192 offset1:200
	global_load_dwordx4 v[34:37], v[26:27], off offset:16
	s_nop 0
	global_load_dwordx4 v[26:29], v[26:27], off
	s_nop 0
	global_load_dwordx4 v[38:41], v[42:43], off offset:16
	s_nop 0
	global_load_dwordx4 v[42:45], v[42:43], off
	s_waitcnt vmcnt(0) lgkmcnt(0)
; __device__ __forceinline__ u32x2 s5_load_u(const bf16_t* U, int t0, int g, int lane) { if (t0 > T - 16) t0 = T - 16; return *(const u32x2*)(U + (size_t)(t0 + (lane >> 2)) * D + g * 16 + (lane & 3) * 4); }
; __device__ __forceinline__ f32x4 s5_u_f32(const u32x2 w) { return (f32x4){bflo(w.x), bfhi(w.x), bflo(w.y), bfhi(w.y)}; }
; __device__ __forceinline__ void s5_item_setup(const S5Params& P, int g, int lane, LAS unsigned char* wlds, S5Item& L) {
;     ...
;     for (int f = 0; f < 8; ++f) {
;         const int pp = 16 * f + (lane & 15), p = pp >> 1; const bool im = pp & 1;
;         const float zr = zt[p * 2], zi = zt[p * 2 + 1];
;         const f32x4* br = (const f32x4*)(P.b_re + (size_t)(g * 64 + p) * 16 + i0); const f32x4* bi = (const f32x4*)(P.b_im + (size_t)(g * 64 + p) * 16 + i0);
;         float v[8];
; #pragma unroll
;         for (int q = 0; q < 2; ++q) { const f32x4 r = br[q], m = bi[q];
; #pragma unroll
;             for (int j = 0; j < 4; ++j) v[q * 4 + j] = im ? (zr * m[j] + zi * r[j]) : (zr * r[j] - zi * m[j]); }
;         u32x4 w;
; #pragma unroll
;         for (int q = 0; q < 4; ++q) { const unsigned h2 = cvt_pk_bf16(v[2 * q], v[2 * q + 1]);
;             const float r0 = v[2 * q] - bflo(h2), r1 = v[2 * q + 1] - bfhi(h2); w[q] = lo_half ? cvt_pk_bf16(r0, r1) : h2; }
;         L.bf[f] = __builtin_bit_cast(bf16x8, w);
;     }
; __device__ __forceinline__ void s5_scan1(LAS unsigned char* lds, const S5Params& P, const bf16_t* U, float* ES, int bid, int G) {
;     ...
;         u32x2 uq0 = s5_load_u(U, c * S5_L, g, lane), uq1 = s5_load_u(U, c * S5_L + 16, g, lane), uq2 = s5_load_u(U, c * S5_L + 32, g, lane), uq3 = s5_load_u(U, c * S5_L + 48, g, lane);
;         for (int t0 = c * S5_L; t0 < (c + 1) * S5_L; t0 += 16) {
;             const f32x4 ucur = s5_u_f32(uq0);
;             uq0 = uq1; uq1 = uq2; uq2 = uq3; uq3 = s5_load_u(U, t0 + 64, g, lane);
	v_pk_mul_f32 v[46:47], v[32:33], v[42:43] op_sel:[1,0]
	v_pk_mul_f32 v[42:43], v[32:33], v[42:43] op_sel_hi:[0,1]
	v_pk_fma_f32 v[46:47], v[32:33], v[26:27], v[46:47] op_sel_hi:[0,1,1] neg_lo:[0,0,1] neg_hi:[0,0,1]
	v_pk_fma_f32 v[26:27], v[32:33], v[26:27], v[42:43] op_sel:[1,0,0]
	s_nop 0
	v_cndmask_b32_e64 v27, v27, v47, s[6:7]
	v_cndmask_b32_e64 v26, v26, v46, s[6:7]
	v_cvt_pk_bf16_f32 v46, v26, v27
	v_lshlrev_b32_e32 v42, 16, v46
	v_and_b32_e32 v43, 0xffff0000, v46
	v_pk_add_f32 v[26:27], v[26:27], v[42:43] neg_lo:[0,1] neg_hi:[0,1]
	v_pk_mul_f32 v[42:43], v[32:33], v[44:45] op_sel:[1,0]
	v_pk_mul_f32 v[44:45], v[32:33], v[44:45] op_sel_hi:[0,1]
	v_pk_fma_f32 v[42:43], v[32:33], v[28:29], v[42:43] op_sel_hi:[0,1,1] neg_lo:[0,0,1] neg_hi:[0,0,1]
	v_pk_fma_f32 v[28:29], v[32:33], v[28:29], v[44:45] op_sel:[1,0,0]
	v_cvt_pk_bf16_f32 v26, v26, v27
	v_cndmask_b32_e64 v29, v29, v43, s[6:7]
	v_cndmask_b32_e64 v28, v28, v42, s[6:7]
	v_cvt_pk_bf16_f32 v27, v28, v29
	v_lshlrev_b32_e32 v42, 16, v27
	v_and_b32_e32 v43, 0xffff0000, v27
	v_pk_add_f32 v[28:29], v[28:29], v[42:43] neg_lo:[0,1] neg_hi:[0,1]
	v_cndmask_b32_e64 v26, v46, v26, s[4:5]
	v_cvt_pk_bf16_f32 v28, v28, v29
	v_cndmask_b32_e64 v27, v27, v28, s[4:5]
	v_pk_mul_f32 v[28:29], v[32:33], v[38:39] op_sel:[1,0]
	v_pk_mul_f32 v[38:39], v[32:33], v[38:39] op_sel_hi:[0,1]
	v_pk_fma_f32 v[28:29], v[32:33], v[34:35], v[28:29] op_sel_hi:[0,1,1] neg_lo:[0,0,1] neg_hi:[0,0,1]
	v_pk_fma_f32 v[34:35], v[32:33], v[34:35], v[38:39] op_sel:[1,0,0]
	s_nop 0
	v_cndmask_b32_e64 v29, v35, v29, s[6:7]
	v_cndmask_b32_e64 v28, v34, v28, s[6:7]
	v_cvt_pk_bf16_f32 v38, v28, v29
	v_lshlrev_b32_e32 v34, 16, v38
	v_and_b32_e32 v35, 0xffff0000, v38
	v_pk_add_f32 v[28:29], v[28:29], v[34:35] neg_lo:[0,1] neg_hi:[0,1]
	v_pk_mul_f32 v[34:35], v[32:33], v[40:41] op_sel:[1,0]
	v_cvt_pk_bf16_f32 v28, v28, v29
	v_cndmask_b32_e64 v28, v38, v28, s[4:5]
	v_pk_mul_f32 v[38:39], v[32:33], v[40:41] op_sel_hi:[0,1]
	v_pk_fma_f32 v[34:35], v[32:33], v[36:37], v[34:35] op_sel_hi:[0,1,1] neg_lo:[0,0,1] neg_hi:[0,0,1]
	v_pk_fma_f32 v[32:33], v[32:33], v[36:37], v[38:39] op_sel:[1,0,0]
	s_nop 0
	v_cndmask_b32_e64 v33, v33, v35, s[6:7]
	v_cndmask_b32_e64 v32, v32, v34, s[6:7]
	v_cvt_pk_bf16_f32 v29, v32, v33
	v_lshlrev_b32_e32 v34, 16, v29
	v_and_b32_e32 v35, 0xffff0000, v29
	v_pk_add_f32 v[32:33], v[32:33], v[34:35] neg_lo:[0,1] neg_hi:[0,1]
	s_nop 0
	v_cvt_pk_bf16_f32 v32, v32, v33
	v_cndmask_b32_e64 v29, v29, v32, s[4:5]
	v_or_b32_e32 v32, s68, v78
	v_lshlrev_b32_e32 v32, 6, v32
	v_mov_b32_e32 v33, v0
	v_lshl_add_u64 v[38:39], v[56:57], 0, v[32:33]
	v_lshl_add_u64 v[32:33], v[58:59], 0, v[32:33]
	global_load_dwordx4 v[34:37], v[38:39], off offset:16
	global_load_dwordx4 v[42:45], v[38:39], off
	s_nop 0
	global_load_dwordx4 v[38:41], v[32:33], off offset:16
	global_load_dwordx4 v[46:49], v[32:33], off
	s_waitcnt vmcnt(0)
	v_pk_mul_f32 v[32:33], v[30:31], v[46:47] op_sel:[1,0]
	v_pk_mul_f32 v[46:47], v[30:31], v[46:47] op_sel_hi:[0,1]
	v_pk_fma_f32 v[32:33], v[30:31], v[42:43], v[32:33] op_sel_hi:[0,1,1] neg_lo:[0,0,1] neg_hi:[0,0,1]
	v_pk_fma_f32 v[42:43], v[30:31], v[42:43], v[46:47] op_sel:[1,0,0]
	s_nop 0
	v_cndmask_b32_e64 v33, v43, v33, s[6:7]
	v_cndmask_b32_e64 v32, v42, v32, s[6:7]
	v_cvt_pk_bf16_f32 v46, v32, v33
	v_lshlrev_b32_e32 v42, 16, v46
	v_and_b32_e32 v43, 0xffff0000, v46
	v_pk_add_f32 v[32:33], v[32:33], v[42:43] neg_lo:[0,1] neg_hi:[0,1]
	v_pk_mul_f32 v[42:43], v[30:31], v[48:49] op_sel:[1,0]
	v_cvt_pk_bf16_f32 v32, v32, v33
	v_cndmask_b32_e64 v32, v46, v32, s[4:5]
	v_pk_mul_f32 v[46:47], v[30:31], v[48:49] op_sel_hi:[0,1]
	v_pk_fma_f32 v[42:43], v[30:31], v[44:45], v[42:43] op_sel_hi:[0,1,1] neg_lo:[0,0,1] neg_hi:[0,0,1]
	v_pk_fma_f32 v[44:45], v[30:31], v[44:45], v[46:47] op_sel:[1,0,0]
	s_nop 0
	v_cndmask_b32_e64 v43, v45, v43, s[6:7]
	v_cndmask_b32_e64 v42, v44, v42, s[6:7]
	v_cvt_pk_bf16_f32 v33, v42, v43
	v_lshlrev_b32_e32 v44, 16, v33
	v_and_b32_e32 v45, 0xffff0000, v33
	v_pk_add_f32 v[42:43], v[42:43], v[44:45] neg_lo:[0,1] neg_hi:[0,1]
	s_nop 0
	v_cvt_pk_bf16_f32 v42, v42, v43
	v_cndmask_b32_e64 v33, v33, v42, s[4:5]
	v_pk_mul_f32 v[42:43], v[30:31], v[38:39] op_sel:[1,0]
	v_pk_mul_f32 v[38:39], v[30:31], v[38:39] op_sel_hi:[0,1]
	v_pk_fma_f32 v[42:43], v[30:31], v[34:35], v[42:43] op_sel_hi:[0,1,1] neg_lo:[0,0,1] neg_hi:[0,0,1]
	v_pk_fma_f32 v[34:35], v[30:31], v[34:35], v[38:39] op_sel:[1,0,0]
	s_nop 0
	v_cndmask_b32_e64 v35, v35, v43, s[6:7]
	v_cndmask_b32_e64 v34, v34, v42, s[6:7]
	v_cvt_pk_bf16_f32 v42, v34, v35
	v_lshlrev_b32_e32 v38, 16, v42
	v_and_b32_e32 v39, 0xffff0000, v42
	v_pk_add_f32 v[34:35], v[34:35], v[38:39] neg_lo:[0,1] neg_hi:[0,1]
	v_pk_mul_f32 v[38:39], v[30:31], v[40:41] op_sel:[1,0]
	v_pk_mul_f32 v[40:41], v[30:31], v[40:41] op_sel_hi:[0,1]
	v_pk_fma_f32 v[38:39], v[30:31], v[36:37], v[38:39] op_sel_hi:[0,1,1] neg_lo:[0,0,1] neg_hi:[0,0,1]
	v_pk_fma_f32 v[30:31], v[30:31], v[36:37], v[40:41] op_sel:[1,0,0]
	v_cvt_pk_bf16_f32 v34, v34, v35
	v_cndmask_b32_e64 v31, v31, v39, s[6:7]
	v_cndmask_b32_e64 v30, v30, v38, s[6:7]
	v_cvt_pk_bf16_f32 v35, v30, v31
	v_lshlrev_b32_e32 v36, 16, v35
	v_and_b32_e32 v37, 0xffff0000, v35
	v_pk_add_f32 v[30:31], v[30:31], v[36:37] neg_lo:[0,1] neg_hi:[0,1]
	v_cndmask_b32_e64 v34, v42, v34, s[4:5]
	v_cvt_pk_bf16_f32 v30, v30, v31
	v_cndmask_b32_e64 v35, v35, v30, s[4:5]
	v_mov_b32_e32 v30, v65
	v_mov_b32_e32 v31, v62
	v_mov_b32_e32 v36, v62
	v_mov_b32_e32 v37, v65
	v_mov_b64_e32 v[94:95], v[76:77]
	v_mov_b64_e32 v[96:97], v[72:73]
	v_mov_b64_e32 v[98:99], v[68:69]
	v_mov_b64_e32 v[100:101], v[70:71]
; #define LAS __attribute__((address_space(3)))
; #define LDS_WAIT() asm volatile("s_waitcnt lgkmcnt(0)" ::: "memory")
; __device__ __forceinline__ u32x2 s5_load_u(const bf16_t* U, int t0, int g, int lane) { if (t0 > T - 16) t0 = T - 16; return *(const u32x2*)(U + (size_t)(t0 + (lane >> 2)) * D + g * 16 + (lane & 3) * 4); }
; __device__ __forceinline__ f32x4 s5_u_f32(const u32x2 w) { return (f32x4){bflo(w.x), bfhi(w.x), bflo(w.y), bfhi(w.y)}; }
; __device__ __forceinline__ void s5_bu_tile(const S5Item& L, const f32x4 ucur, LAS unsigned char* wlds, int lane) {
;     LAS float* ut = (LAS float*)(wlds + S5_OFF_U);
;     *(LAS f32x4*)(ut + (lane >> 2) * 16 + (lane & 3) * 4) = ucur;
;     LDS_WAIT(); __builtin_amdgcn_wave_barrier();
;     const LAS f32x4* up = (const LAS f32x4*)(ut + (lane & 15) * 16 + ((lane >> 4) & 1) * 8);
;     const f32x4 u0 = up[0], u1 = up[1];
;     u32x4 w; w.x = cvt_pk_bf16(u0[0], u0[1]); w.y = cvt_pk_bf16(u0[2], u0[3]); w.z = cvt_pk_bf16(u1[0], u1[1]); w.w = cvt_pk_bf16(u1[2], u1[3]);
;     const bf16x8 uf = __builtin_bit_cast(bf16x8, w);
; #pragma unroll
;     for (int f = 0; f < 8; ++f) {
;         f32x4 d = (f32x4){0.f, 0.f, 0.f, 0.f};
;         d = __builtin_amdgcn_mfma_f32_16x16x32_bf16(L.bf[f], uf, d, 0, 0, 0);
;         *(LAS f32x4*)(wlds + (lane & 15) * S5_BU_STRIDE + (16 * f + (lane >> 4) * 4) * 4) = d;
;     }
;     LDS_WAIT(); __builtin_amdgcn_wave_barrier();
; __device__ __forceinline__ void s5_scan1(LAS unsigned char* lds, const S5Params& P, const bf16_t* U, float* ES, int bid, int G) {
;     ...
;         for (int t0 = c * S5_L; t0 < (c + 1) * S5_L; t0 += 16) {
;             const f32x4 ucur = s5_u_f32(uq0);
;             uq0 = uq1; uq1 = uq2; uq2 = uq3; uq3 = s5_load_u(U, t0 + 64, g, lane);
;             s5_bu_tile(L, ucur, wlds, lane);
; #pragma unroll
;             for (int i = 0; i < 16; ++i) { const f32x2 bu = *(const LAS f32x2*)(wlds + i * S5_BU_STRIDE + lane * 8);
;                 const float nre = L.abr * sre - L.abi * sim + bu[0], nim = L.abr * sim + L.abi * sre + bu[1]; sre = nre; sim = nim; }
.LBB0_1179:
	s_waitcnt vmcnt(3)
	s_min_i32 s1, s8, 0x1fb0
	v_add_u32_e32 v44, s1, v88
	v_ashrrev_i32_e32 v45, 31, v44
	v_lshlrev_b32_e32 v40, 16, v94
	v_and_b32_e32 v41, 0xffff0000, v94
	v_lshlrev_b32_e32 v42, 16, v95
	v_and_b32_e32 v43, 0xffff0000, v95
	v_lshlrev_b64 v[44:45], 12, v[44:45]
	v_lshl_add_u64 v[44:45], v[66:67], 0, v[44:45]
	ds_write_b128 v89, v[40:43] offset:12800
	global_load_dwordx2 v[94:95], v[44:45], off
	s_waitcnt lgkmcnt(0)
	ds_read_b128 v[40:43], v90 offset:12800
	ds_read_b128 v[44:47], v90 offset:12816
	v_add_u32_e32 v61, 0x800, v91
	s_add_i32 s1, s8, 16
	s_cmp_ge_i32 s8, s0
	s_waitcnt lgkmcnt(1)
	v_cvt_pk_bf16_f32 v40, v40, v41
	v_cvt_pk_bf16_f32 v41, v42, v43
	s_waitcnt lgkmcnt(0)
	v_cvt_pk_bf16_f32 v42, v44, v45
	v_cvt_pk_bf16_f32 v43, v46, v47
	s_mov_b32 s8, s1
	s_nop 0
	v_mfma_f32_16x16x32_bf16 v[44:47], v[32:35], v[40:43], 0
	s_nop 7
	ds_write_b128 v51, v[44:47]
	v_mfma_f32_16x16x32_bf16 v[44:47], v[26:29], v[40:43], 0
	s_nop 7
	ds_write_b128 v51, v[44:47] offset:64
	v_mfma_f32_16x16x32_bf16 v[44:47], v[22:25], v[40:43], 0
	s_nop 7
	ds_write_b128 v51, v[44:47] offset:128
	v_mfma_f32_16x16x32_bf16 v[44:47], v[18:21], v[40:43], 0
	s_nop 7
	ds_write_b128 v51, v[44:47] offset:192
	v_mfma_f32_16x16x32_bf16 v[44:47], v[14:17], v[40:43], 0
	s_nop 7
	ds_write_b128 v51, v[44:47] offset:256
	v_mfma_f32_16x16x32_bf16 v[44:47], v[10:13], v[40:43], 0
	s_nop 7
	ds_write_b128 v51, v[44:47] offset:320
	v_mfma_f32_16x16x32_bf16 v[44:47], v[6:9], v[40:43], 0
	v_mfma_f32_16x16x32_bf16 v[40:43], v[2:5], v[40:43], 0
	s_nop 6
	ds_write_b128 v51, v[44:47] offset:384
	ds_write_b128 v51, v[40:43] offset:448
	s_waitcnt lgkmcnt(0)
	ds_read2_b64 v[40:43], v91 offset1:66
	v_pk_mul_f32 v[44:45], v[64:65], v[74:75]
	s_nop 0
	v_pk_fma_f32 v[46:47], v[62:63], v[74:75], v[44:45] op_sel:[0,0,1] op_sel_hi:[1,1,0] neg_lo:[0,0,1] neg_hi:[0,0,1]
	v_pk_fma_f32 v[44:45], v[62:63], v[74:75], v[44:45] op_sel:[0,0,1] op_sel_hi:[1,1,0]
	ds_read2_b64 v[74:77], v61 offset0:8 offset1:74
	v_mov_b32_e32 v47, v45
	s_waitcnt lgkmcnt(1)
	v_pk_add_f32 v[40:41], v[46:47], v[40:41]
	s_nop 0
	v_pk_mul_f32 v[44:45], v[64:65], v[40:41]
	s_nop 0
	v_pk_fma_f32 v[48:49], v[62:63], v[40:41], v[44:45] op_sel:[0,0,1] op_sel_hi:[1,1,0] neg_lo:[0,0,1] neg_hi:[0,0,1]
	v_pk_fma_f32 v[40:41], v[62:63], v[40:41], v[44:45] op_sel:[0,0,1] op_sel_hi:[1,1,0]
	ds_read2_b64 v[44:47], v91 offset0:132 offset1:198
	v_mov_b32_e32 v49, v41
	v_pk_add_f32 v[40:41], v[42:43], v[48:49]
	s_nop 0
	v_pk_mul_f32 v[42:43], v[64:65], v[40:41]
	s_nop 0
	v_pk_fma_f32 v[48:49], v[62:63], v[40:41], v[42:43] op_sel:[0,0,1] op_sel_hi:[1,1,0]
	v_pk_fma_f32 v[40:41], v[62:63], v[40:41], v[42:43] op_sel:[0,0,1] op_sel_hi:[1,1,0] neg_lo:[0,0,1] neg_hi:[0,0,1]
	s_nop 0
	v_mov_b32_e32 v41, v49
	s_waitcnt lgkmcnt(0)
	v_pk_add_f32 v[40:41], v[44:45], v[40:41]
	s_nop 0
	v_pk_mul_f32 v[42:43], v[64:65], v[40:41]
	s_nop 0
	v_pk_fma_f32 v[44:45], v[62:63], v[40:41], v[42:43] op_sel:[0,0,1] op_sel_hi:[1,1,0]
	v_pk_fma_f32 v[40:41], v[62:63], v[40:41], v[42:43] op_sel:[0,0,1] op_sel_hi:[1,1,0] neg_lo:[0,0,1] neg_hi:[0,0,1]
	s_nop 0
	v_mov_b32_e32 v41, v45
	v_pk_add_f32 v[40:41], v[46:47], v[40:41]
	s_nop 0
	v_pk_mul_f32 v[42:43], v[64:65], v[40:41]
	s_nop 0
	v_pk_fma_f32 v[44:45], v[62:63], v[40:41], v[42:43] op_sel:[0,0,1] op_sel_hi:[1,1,0]
	v_pk_fma_f32 v[40:41], v[62:63], v[40:41], v[42:43] op_sel:[0,0,1] op_sel_hi:[1,1,0] neg_lo:[0,0,1] neg_hi:[0,0,1]
	s_nop 0
	v_mov_b32_e32 v41, v45
	v_pk_add_f32 v[40:41], v[74:75], v[40:41]
	s_nop 0
	v_mul_f32_e32 v42, v37, v41
	v_pk_fma_f32 v[48:49], v[36:37], v[40:41], v[42:43] op_sel_hi:[1,1,0] neg_lo:[0,0,1] neg_hi:[0,0,1]
	v_mul_f32_e32 v42, v30, v40
	v_pk_fma_f32 v[74:75], v[30:31], v[40:41], v[42:43] op_sel_hi:[1,1,0]
	ds_read2_b64 v[40:43], v61 offset0:140 offset1:206
	v_mov_b32_e32 v49, v75
	v_pk_add_f32 v[48:49], v[76:77], v[48:49]
	v_add_u32_e32 v61, 0x1000, v91
	v_pk_mul_f32 v[74:75], v[64:65], v[48:49]
	ds_read2_b64 v[44:47], v61 offset0:16 offset1:82
	v_pk_fma_f32 v[76:77], v[62:63], v[48:49], v[74:75] op_sel:[0,0,1] op_sel_hi:[1,1,0] neg_lo:[0,0,1] neg_hi:[0,0,1]
	v_pk_fma_f32 v[48:49], v[62:63], v[48:49], v[74:75] op_sel:[0,0,1] op_sel_hi:[1,1,0]
	s_nop 0
	v_mov_b32_e32 v77, v49
	s_waitcnt lgkmcnt(1)
	v_pk_add_f32 v[40:41], v[40:41], v[76:77]
	s_nop 0
	v_pk_mul_f32 v[48:49], v[64:65], v[40:41]
	s_nop 0
	v_pk_fma_f32 v[74:75], v[62:63], v[40:41], v[48:49] op_sel:[0,0,1] op_sel_hi:[1,1,0] neg_lo:[0,0,1] neg_hi:[0,0,1]
	v_pk_fma_f32 v[40:41], v[62:63], v[40:41], v[48:49] op_sel:[0,0,1] op_sel_hi:[1,1,0]
	s_nop 0
	v_mov_b32_e32 v75, v41
	v_pk_add_f32 v[40:41], v[42:43], v[74:75]
	s_nop 0
	v_pk_mul_f32 v[42:43], v[64:65], v[40:41]
	s_nop 0
	v_pk_fma_f32 v[48:49], v[62:63], v[40:41], v[42:43] op_sel:[0,0,1] op_sel_hi:[1,1,0] neg_lo:[0,0,1] neg_hi:[0,0,1]
	v_pk_fma_f32 v[40:41], v[62:63], v[40:41], v[42:43] op_sel:[0,0,1] op_sel_hi:[1,1,0]
	s_nop 0
	v_mov_b32_e32 v49, v41
	s_waitcnt lgkmcnt(0)
	v_pk_add_f32 v[44:45], v[44:45], v[48:49]
	ds_read2_b64 v[40:43], v61 offset0:148 offset1:214
	v_pk_mul_f32 v[48:49], v[64:65], v[44:45]
	v_add_u32_e32 v61, 0x1800, v91
	v_pk_fma_f32 v[92:93], v[62:63], v[44:45], v[48:49] op_sel:[0,0,1] op_sel_hi:[1,1,0] neg_lo:[0,0,1] neg_hi:[0,0,1]
	v_pk_fma_f32 v[44:45], v[62:63], v[44:45], v[48:49] op_sel:[0,0,1] op_sel_hi:[1,1,0]
	ds_read2_b64 v[74:77], v61 offset0:24 offset1:90
	v_mov_b32_e32 v93, v45
	v_pk_add_f32 v[44:45], v[46:47], v[92:93]
	s_nop 0
	v_pk_mul_f32 v[46:47], v[64:65], v[44:45]
	s_nop 0
	v_pk_fma_f32 v[48:49], v[62:63], v[44:45], v[46:47] op_sel:[0,0,1] op_sel_hi:[1,1,0] neg_lo:[0,0,1] neg_hi:[0,0,1]
	v_pk_fma_f32 v[44:45], v[62:63], v[44:45], v[46:47] op_sel:[0,0,1] op_sel_hi:[1,1,0]
	s_nop 0
	v_mov_b32_e32 v49, v45
	s_waitcnt lgkmcnt(1)
; #define LAS __attribute__((address_space(3)))
; #define LDS_WAIT() asm volatile("s_waitcnt lgkmcnt(0)" ::: "memory")
; __device__ __forceinline__ u32x2 s5_load_u(const bf16_t* U, int t0, int g, int lane) { if (t0 > T - 16) t0 = T - 16; return *(const u32x2*)(U + (size_t)(t0 + (lane >> 2)) * D + g * 16 + (lane & 3) * 4); }
; __device__ __forceinline__ f32x4 s5_u_f32(const u32x2 w) { return (f32x4){bflo(w.x), bfhi(w.x), bflo(w.y), bfhi(w.y)}; }
; __device__ __forceinline__ void s5_bu_tile(const S5Item& L, const f32x4 ucur, LAS unsigned char* wlds, int lane) {
;     LAS float* ut = (LAS float*)(wlds + S5_OFF_U);
;     *(LAS f32x4*)(ut + (lane >> 2) * 16 + (lane & 3) * 4) = ucur;
;     LDS_WAIT(); __builtin_amdgcn_wave_barrier();
;     const LAS f32x4* up = (const LAS f32x4*)(ut + (lane & 15) * 16 + ((lane >> 4) & 1) * 8);
;     const f32x4 u0 = up[0], u1 = up[1];
;     u32x4 w; w.x = cvt_pk_bf16(u0[0], u0[1]); w.y = cvt_pk_bf16(u0[2], u0[3]); w.z = cvt_pk_bf16(u1[0], u1[1]); w.w = cvt_pk_bf16(u1[2], u1[3]);
;     const bf16x8 uf = __builtin_bit_cast(bf16x8, w);
; #pragma unroll
;     for (int f = 0; f < 8; ++f) {
;         f32x4 d = (f32x4){0.f, 0.f, 0.f, 0.f};
;         d = __builtin_amdgcn_mfma_f32_16x16x32_bf16(L.bf[f], uf, d, 0, 0, 0);
;         *(LAS f32x4*)(wlds + (lane & 15) * S5_BU_STRIDE + (16 * f + (lane >> 4) * 4) * 4) = d;
;     }
;     LDS_WAIT(); __builtin_amdgcn_wave_barrier();
; __device__ __forceinline__ void s5_scan1(LAS unsigned char* lds, const S5Params& P, const bf16_t* U, float* ES, int bid, int G) {
;     ...
;         for (int t0 = c * S5_L; t0 < (c + 1) * S5_L; t0 += 16) {
;             const f32x4 ucur = s5_u_f32(uq0);
;             uq0 = uq1; uq1 = uq2; uq2 = uq3; uq3 = s5_load_u(U, t0 + 64, g, lane);
;             s5_bu_tile(L, ucur, wlds, lane);
; #pragma unroll
;             for (int i = 0; i < 16; ++i) { const f32x2 bu = *(const LAS f32x2*)(wlds + i * S5_BU_STRIDE + lane * 8);
;                 const float nre = L.abr * sre - L.abi * sim + bu[0], nim = L.abr * sim + L.abi * sre + bu[1]; sre = nre; sim = nim; }
	v_pk_add_f32 v[40:41], v[40:41], v[48:49]
	s_nop 0
	v_pk_mul_f32 v[44:45], v[64:65], v[40:41]
	s_nop 0
	v_pk_fma_f32 v[46:47], v[62:63], v[40:41], v[44:45] op_sel:[0,0,1] op_sel_hi:[1,1,0] neg_lo:[0,0,1] neg_hi:[0,0,1]
	v_pk_fma_f32 v[40:41], v[62:63], v[40:41], v[44:45] op_sel:[0,0,1] op_sel_hi:[1,1,0]
	s_nop 0
	v_mov_b32_e32 v47, v41
	v_pk_add_f32 v[40:41], v[42:43], v[46:47]
	s_nop 0
	v_pk_mul_f32 v[42:43], v[64:65], v[40:41]
	s_nop 0
	v_pk_fma_f32 v[44:45], v[62:63], v[40:41], v[42:43] op_sel:[0,0,1] op_sel_hi:[1,1,0] neg_lo:[0,0,1] neg_hi:[0,0,1]
	v_pk_fma_f32 v[40:41], v[62:63], v[40:41], v[42:43] op_sel:[0,0,1] op_sel_hi:[1,1,0]
	s_nop 0
	v_mov_b32_e32 v45, v41
	s_waitcnt lgkmcnt(0)
	v_pk_add_f32 v[44:45], v[74:75], v[44:45]
	ds_read2_b64 v[40:43], v61 offset0:156 offset1:222
	v_pk_mul_f32 v[46:47], v[64:65], v[44:45]
	s_waitcnt lgkmcnt(0)
	s_nop 0
	v_pk_fma_f32 v[48:49], v[62:63], v[44:45], v[46:47] op_sel:[0,0,1] op_sel_hi:[1,1,0] neg_lo:[0,0,1] neg_hi:[0,0,1]
	v_pk_fma_f32 v[44:45], v[62:63], v[44:45], v[46:47] op_sel:[0,0,1] op_sel_hi:[1,1,0]
	s_nop 0
	v_mov_b32_e32 v49, v45
	v_pk_add_f32 v[44:45], v[76:77], v[48:49]
	v_pk_mul_f32 v[46:47], v[64:65], v[44:45]
	v_pk_fma_f32 v[48:49], v[62:63], v[44:45], v[46:47] op_sel:[0,0,1] op_sel_hi:[1,1,0] neg_lo:[0,0,1] neg_hi:[0,0,1]
	v_pk_fma_f32 v[44:45], v[62:63], v[44:45], v[46:47] op_sel:[0,0,1] op_sel_hi:[1,1,0]
	s_nop 0
	v_mov_b32_e32 v49, v45
	s_waitcnt lgkmcnt(0)
	v_pk_add_f32 v[40:41], v[40:41], v[48:49]
	s_nop 0
	v_pk_mul_f32 v[44:45], v[64:65], v[40:41]
	s_nop 0
	v_pk_fma_f32 v[46:47], v[62:63], v[40:41], v[44:45] op_sel:[0,0,1] op_sel_hi:[1,1,0] neg_lo:[0,0,1] neg_hi:[0,0,1]
	v_pk_fma_f32 v[40:41], v[62:63], v[40:41], v[44:45] op_sel:[0,0,1] op_sel_hi:[1,1,0]
	s_nop 0
	v_mov_b32_e32 v47, v41
	v_pk_add_f32 v[74:75], v[42:43], v[46:47]
	s_waitcnt vmcnt(3)
	s_min_i32 s1, s8, 0x1fb0
	v_add_u32_e32 v44, s1, v88
	v_ashrrev_i32_e32 v45, 31, v44
	v_lshlrev_b32_e32 v40, 16, v96
	v_and_b32_e32 v41, 0xffff0000, v96
	v_lshlrev_b32_e32 v42, 16, v97
	v_and_b32_e32 v43, 0xffff0000, v97
	v_lshlrev_b64 v[44:45], 12, v[44:45]
	v_lshl_add_u64 v[44:45], v[66:67], 0, v[44:45]
	ds_write_b128 v89, v[40:43] offset:12800
	global_load_dwordx2 v[96:97], v[44:45], off
	s_waitcnt lgkmcnt(0)
	ds_read_b128 v[40:43], v90 offset:12800
	ds_read_b128 v[44:47], v90 offset:12816
	v_add_u32_e32 v61, 0x800, v91
	s_add_i32 s1, s8, 16
	s_cmp_ge_i32 s8, s0
	s_waitcnt lgkmcnt(1)
	v_cvt_pk_bf16_f32 v40, v40, v41
	v_cvt_pk_bf16_f32 v41, v42, v43
	s_waitcnt lgkmcnt(0)
	v_cvt_pk_bf16_f32 v42, v44, v45
	v_cvt_pk_bf16_f32 v43, v46, v47
	s_mov_b32 s8, s1
	s_nop 0
	v_mfma_f32_16x16x32_bf16 v[44:47], v[32:35], v[40:43], 0
	s_nop 7
	ds_write_b128 v51, v[44:47]
	v_mfma_f32_16x16x32_bf16 v[44:47], v[26:29], v[40:43], 0
	s_nop 7
	ds_write_b128 v51, v[44:47] offset:64
	v_mfma_f32_16x16x32_bf16 v[44:47], v[22:25], v[40:43], 0
	s_nop 7
	ds_write_b128 v51, v[44:47] offset:128
	v_mfma_f32_16x16x32_bf16 v[44:47], v[18:21], v[40:43], 0
	s_nop 7
	ds_write_b128 v51, v[44:47] offset:192
	v_mfma_f32_16x16x32_bf16 v[44:47], v[14:17], v[40:43], 0
	s_nop 7
	ds_write_b128 v51, v[44:47] offset:256
	v_mfma_f32_16x16x32_bf16 v[44:47], v[10:13], v[40:43], 0
	s_nop 7
	ds_write_b128 v51, v[44:47] offset:320
	v_mfma_f32_16x16x32_bf16 v[44:47], v[6:9], v[40:43], 0
	v_mfma_f32_16x16x32_bf16 v[40:43], v[2:5], v[40:43], 0
	s_nop 6
	ds_write_b128 v51, v[44:47] offset:384
	ds_write_b128 v51, v[40:43] offset:448
	s_waitcnt lgkmcnt(0)
	ds_read2_b64 v[40:43], v91 offset1:66
	v_pk_mul_f32 v[44:45], v[64:65], v[74:75]
	s_nop 0
	v_pk_fma_f32 v[46:47], v[62:63], v[74:75], v[44:45] op_sel:[0,0,1] op_sel_hi:[1,1,0] neg_lo:[0,0,1] neg_hi:[0,0,1]
	v_pk_fma_f32 v[44:45], v[62:63], v[74:75], v[44:45] op_sel:[0,0,1] op_sel_hi:[1,1,0]
	ds_read2_b64 v[74:77], v61 offset0:8 offset1:74
	v_mov_b32_e32 v47, v45
	s_waitcnt lgkmcnt(1)
	v_pk_add_f32 v[40:41], v[46:47], v[40:41]
	s_nop 0
	v_pk_mul_f32 v[44:45], v[64:65], v[40:41]
	s_nop 0
	v_pk_fma_f32 v[48:49], v[62:63], v[40:41], v[44:45] op_sel:[0,0,1] op_sel_hi:[1,1,0] neg_lo:[0,0,1] neg_hi:[0,0,1]
	v_pk_fma_f32 v[40:41], v[62:63], v[40:41], v[44:45] op_sel:[0,0,1] op_sel_hi:[1,1,0]
	ds_read2_b64 v[44:47], v91 offset0:132 offset1:198
	v_mov_b32_e32 v49, v41
	v_pk_add_f32 v[40:41], v[42:43], v[48:49]
	s_nop 0
	v_pk_mul_f32 v[42:43], v[64:65], v[40:41]
	s_nop 0
	v_pk_fma_f32 v[48:49], v[62:63], v[40:41], v[42:43] op_sel:[0,0,1] op_sel_hi:[1,1,0]
	v_pk_fma_f32 v[40:41], v[62:63], v[40:41], v[42:43] op_sel:[0,0,1] op_sel_hi:[1,1,0] neg_lo:[0,0,1] neg_hi:[0,0,1]
	s_nop 0
	v_mov_b32_e32 v41, v49
	s_waitcnt lgkmcnt(0)
	v_pk_add_f32 v[40:41], v[44:45], v[40:41]
	s_nop 0
	v_pk_mul_f32 v[42:43], v[64:65], v[40:41]
	s_nop 0
	v_pk_fma_f32 v[44:45], v[62:63], v[40:41], v[42:43] op_sel:[0,0,1] op_sel_hi:[1,1,0]
	v_pk_fma_f32 v[40:41], v[62:63], v[40:41], v[42:43] op_sel:[0,0,1] op_sel_hi:[1,1,0] neg_lo:[0,0,1] neg_hi:[0,0,1]
	s_nop 0
	v_mov_b32_e32 v41, v45
	v_pk_add_f32 v[40:41], v[46:47], v[40:41]
	s_nop 0
	v_pk_mul_f32 v[42:43], v[64:65], v[40:41]
	s_nop 0
	v_pk_fma_f32 v[44:45], v[62:63], v[40:41], v[42:43] op_sel:[0,0,1] op_sel_hi:[1,1,0]
	v_pk_fma_f32 v[40:41], v[62:63], v[40:41], v[42:43] op_sel:[0,0,1] op_sel_hi:[1,1,0] neg_lo:[0,0,1] neg_hi:[0,0,1]
	s_nop 0
	v_mov_b32_e32 v41, v45
	v_pk_add_f32 v[40:41], v[74:75], v[40:41]
	s_nop 0
	v_mul_f32_e32 v42, v37, v41
	v_pk_fma_f32 v[48:49], v[36:37], v[40:41], v[42:43] op_sel_hi:[1,1,0] neg_lo:[0,0,1] neg_hi:[0,0,1]
	v_mul_f32_e32 v42, v30, v40
	v_pk_fma_f32 v[74:75], v[30:31], v[40:41], v[42:43] op_sel_hi:[1,1,0]
	ds_read2_b64 v[40:43], v61 offset0:140 offset1:206
	v_mov_b32_e32 v49, v75
	v_pk_add_f32 v[48:49], v[76:77], v[48:49]
	v_add_u32_e32 v61, 0x1000, v91
	v_pk_mul_f32 v[74:75], v[64:65], v[48:49]
	ds_read2_b64 v[44:47], v61 offset0:16 offset1:82
	v_pk_fma_f32 v[76:77], v[62:63], v[48:49], v[74:75] op_sel:[0,0,1] op_sel_hi:[1,1,0] neg_lo:[0,0,1] neg_hi:[0,0,1]
	v_pk_fma_f32 v[48:49], v[62:63], v[48:49], v[74:75] op_sel:[0,0,1] op_sel_hi:[1,1,0]
	s_nop 0
	v_mov_b32_e32 v77, v49
	s_waitcnt lgkmcnt(1)
; #define LAS __attribute__((address_space(3)))
; #define LDS_WAIT() asm volatile("s_waitcnt lgkmcnt(0)" ::: "memory")
; __device__ __forceinline__ u32x2 s5_load_u(const bf16_t* U, int t0, int g, int lane) { if (t0 > T - 16) t0 = T - 16; return *(const u32x2*)(U + (size_t)(t0 + (lane >> 2)) * D + g * 16 + (lane & 3) * 4); }
; __device__ __forceinline__ f32x4 s5_u_f32(const u32x2 w) { return (f32x4){bflo(w.x), bfhi(w.x), bflo(w.y), bfhi(w.y)}; }
; __device__ __forceinline__ void s5_bu_tile(const S5Item& L, const f32x4 ucur, LAS unsigned char* wlds, int lane) {
;     LAS float* ut = (LAS float*)(wlds + S5_OFF_U);
;     *(LAS f32x4*)(ut + (lane >> 2) * 16 + (lane & 3) * 4) = ucur;
;     LDS_WAIT(); __builtin_amdgcn_wave_barrier();
;     const LAS f32x4* up = (const LAS f32x4*)(ut + (lane & 15) * 16 + ((lane >> 4) & 1) * 8);
;     const f32x4 u0 = up[0], u1 = up[1];
;     u32x4 w; w.x = cvt_pk_bf16(u0[0], u0[1]); w.y = cvt_pk_bf16(u0[2], u0[3]); w.z = cvt_pk_bf16(u1[0], u1[1]); w.w = cvt_pk_bf16(u1[2], u1[3]);
;     const bf16x8 uf = __builtin_bit_cast(bf16x8, w);
; #pragma unroll
;     for (int f = 0; f < 8; ++f) {
;         f32x4 d = (f32x4){0.f, 0.f, 0.f, 0.f};
;         d = __builtin_amdgcn_mfma_f32_16x16x32_bf16(L.bf[f], uf, d, 0, 0, 0);
;         *(LAS f32x4*)(wlds + (lane & 15) * S5_BU_STRIDE + (16 * f + (lane >> 4) * 4) * 4) = d;
;     }
;     LDS_WAIT(); __builtin_amdgcn_wave_barrier();
; __device__ __forceinline__ void s5_scan1(LAS unsigned char* lds, const S5Params& P, const bf16_t* U, float* ES, int bid, int G) {
;     ...
;         for (int t0 = c * S5_L; t0 < (c + 1) * S5_L; t0 += 16) {
;             const f32x4 ucur = s5_u_f32(uq0);
;             uq0 = uq1; uq1 = uq2; uq2 = uq3; uq3 = s5_load_u(U, t0 + 64, g, lane);
;             s5_bu_tile(L, ucur, wlds, lane);
; #pragma unroll
;             for (int i = 0; i < 16; ++i) { const f32x2 bu = *(const LAS f32x2*)(wlds + i * S5_BU_STRIDE + lane * 8);
;                 const float nre = L.abr * sre - L.abi * sim + bu[0], nim = L.abr * sim + L.abi * sre + bu[1]; sre = nre; sim = nim; }
	v_pk_add_f32 v[40:41], v[40:41], v[76:77]
	s_nop 0
	v_pk_mul_f32 v[48:49], v[64:65], v[40:41]
	s_nop 0
	v_pk_fma_f32 v[74:75], v[62:63], v[40:41], v[48:49] op_sel:[0,0,1] op_sel_hi:[1,1,0] neg_lo:[0,0,1] neg_hi:[0,0,1]
	v_pk_fma_f32 v[40:41], v[62:63], v[40:41], v[48:49] op_sel:[0,0,1] op_sel_hi:[1,1,0]
	s_nop 0
	v_mov_b32_e32 v75, v41
	v_pk_add_f32 v[40:41], v[42:43], v[74:75]
	s_nop 0
	v_pk_mul_f32 v[42:43], v[64:65], v[40:41]
	s_nop 0
	v_pk_fma_f32 v[48:49], v[62:63], v[40:41], v[42:43] op_sel:[0,0,1] op_sel_hi:[1,1,0] neg_lo:[0,0,1] neg_hi:[0,0,1]
	v_pk_fma_f32 v[40:41], v[62:63], v[40:41], v[42:43] op_sel:[0,0,1] op_sel_hi:[1,1,0]
	s_nop 0
	v_mov_b32_e32 v49, v41
	s_waitcnt lgkmcnt(0)
	v_pk_add_f32 v[44:45], v[44:45], v[48:49]
	ds_read2_b64 v[40:43], v61 offset0:148 offset1:214
	v_pk_mul_f32 v[48:49], v[64:65], v[44:45]
	v_add_u32_e32 v61, 0x1800, v91
	v_pk_fma_f32 v[92:93], v[62:63], v[44:45], v[48:49] op_sel:[0,0,1] op_sel_hi:[1,1,0] neg_lo:[0,0,1] neg_hi:[0,0,1]
	v_pk_fma_f32 v[44:45], v[62:63], v[44:45], v[48:49] op_sel:[0,0,1] op_sel_hi:[1,1,0]
	ds_read2_b64 v[74:77], v61 offset0:24 offset1:90
	v_mov_b32_e32 v93, v45
	v_pk_add_f32 v[44:45], v[46:47], v[92:93]
	s_nop 0
	v_pk_mul_f32 v[46:47], v[64:65], v[44:45]
	s_nop 0
	v_pk_fma_f32 v[48:49], v[62:63], v[44:45], v[46:47] op_sel:[0,0,1] op_sel_hi:[1,1,0] neg_lo:[0,0,1] neg_hi:[0,0,1]
	v_pk_fma_f32 v[44:45], v[62:63], v[44:45], v[46:47] op_sel:[0,0,1] op_sel_hi:[1,1,0]
	s_nop 0
	v_mov_b32_e32 v49, v45
	s_waitcnt lgkmcnt(1)
	v_pk_add_f32 v[40:41], v[40:41], v[48:49]
	s_nop 0
	v_pk_mul_f32 v[44:45], v[64:65], v[40:41]
	s_nop 0
	v_pk_fma_f32 v[46:47], v[62:63], v[40:41], v[44:45] op_sel:[0,0,1] op_sel_hi:[1,1,0] neg_lo:[0,0,1] neg_hi:[0,0,1]
	v_pk_fma_f32 v[40:41], v[62:63], v[40:41], v[44:45] op_sel:[0,0,1] op_sel_hi:[1,1,0]
	s_nop 0
	v_mov_b32_e32 v47, v41
	v_pk_add_f32 v[40:41], v[42:43], v[46:47]
	s_nop 0
	v_pk_mul_f32 v[42:43], v[64:65], v[40:41]
	s_nop 0
	v_pk_fma_f32 v[44:45], v[62:63], v[40:41], v[42:43] op_sel:[0,0,1] op_sel_hi:[1,1,0] neg_lo:[0,0,1] neg_hi:[0,0,1]
	v_pk_fma_f32 v[40:41], v[62:63], v[40:41], v[42:43] op_sel:[0,0,1] op_sel_hi:[1,1,0]
	s_nop 0
	v_mov_b32_e32 v45, v41
	s_waitcnt lgkmcnt(0)
	v_pk_add_f32 v[44:45], v[74:75], v[44:45]
	ds_read2_b64 v[40:43], v61 offset0:156 offset1:222
	v_pk_mul_f32 v[46:47], v[64:65], v[44:45]
	s_waitcnt lgkmcnt(0)
	s_nop 0
	v_pk_fma_f32 v[48:49], v[62:63], v[44:45], v[46:47] op_sel:[0,0,1] op_sel_hi:[1,1,0] neg_lo:[0,0,1] neg_hi:[0,0,1]
	v_pk_fma_f32 v[44:45], v[62:63], v[44:45], v[46:47] op_sel:[0,0,1] op_sel_hi:[1,1,0]
	s_nop 0
	v_mov_b32_e32 v49, v45
	v_pk_add_f32 v[44:45], v[76:77], v[48:49]
	v_pk_mul_f32 v[46:47], v[64:65], v[44:45]
	v_pk_fma_f32 v[48:49], v[62:63], v[44:45], v[46:47] op_sel:[0,0,1] op_sel_hi:[1,1,0] neg_lo:[0,0,1] neg_hi:[0,0,1]
	v_pk_fma_f32 v[44:45], v[62:63], v[44:45], v[46:47] op_sel:[0,0,1] op_sel_hi:[1,1,0]
	s_nop 0
	v_mov_b32_e32 v49, v45
	s_waitcnt lgkmcnt(0)
	v_pk_add_f32 v[40:41], v[40:41], v[48:49]
	s_nop 0
	v_pk_mul_f32 v[44:45], v[64:65], v[40:41]
	s_nop 0
	v_pk_fma_f32 v[46:47], v[62:63], v[40:41], v[44:45] op_sel:[0,0,1] op_sel_hi:[1,1,0] neg_lo:[0,0,1] neg_hi:[0,0,1]
	v_pk_fma_f32 v[40:41], v[62:63], v[40:41], v[44:45] op_sel:[0,0,1] op_sel_hi:[1,1,0]
	s_nop 0
	v_mov_b32_e32 v47, v41
	v_pk_add_f32 v[74:75], v[42:43], v[46:47]
	s_waitcnt vmcnt(3)
	s_min_i32 s1, s8, 0x1fb0
	v_add_u32_e32 v44, s1, v88
	v_ashrrev_i32_e32 v45, 31, v44
	v_lshlrev_b32_e32 v40, 16, v98
	v_and_b32_e32 v41, 0xffff0000, v98
	v_lshlrev_b32_e32 v42, 16, v99
	v_and_b32_e32 v43, 0xffff0000, v99
	v_lshlrev_b64 v[44:45], 12, v[44:45]
	v_lshl_add_u64 v[44:45], v[66:67], 0, v[44:45]
	ds_write_b128 v89, v[40:43] offset:12800
	global_load_dwordx2 v[98:99], v[44:45], off
	s_waitcnt lgkmcnt(0)
	ds_read_b128 v[40:43], v90 offset:12800
	ds_read_b128 v[44:47], v90 offset:12816
	v_add_u32_e32 v61, 0x800, v91
	s_add_i32 s1, s8, 16
	s_cmp_ge_i32 s8, s0
	s_waitcnt lgkmcnt(1)
	v_cvt_pk_bf16_f32 v40, v40, v41
	v_cvt_pk_bf16_f32 v41, v42, v43
	s_waitcnt lgkmcnt(0)
	v_cvt_pk_bf16_f32 v42, v44, v45
	v_cvt_pk_bf16_f32 v43, v46, v47
	s_mov_b32 s8, s1
	s_nop 0
	v_mfma_f32_16x16x32_bf16 v[44:47], v[32:35], v[40:43], 0
	s_nop 7
	ds_write_b128 v51, v[44:47]
	v_mfma_f32_16x16x32_bf16 v[44:47], v[26:29], v[40:43], 0
	s_nop 7
	ds_write_b128 v51, v[44:47] offset:64
	v_mfma_f32_16x16x32_bf16 v[44:47], v[22:25], v[40:43], 0
	s_nop 7
	ds_write_b128 v51, v[44:47] offset:128
	v_mfma_f32_16x16x32_bf16 v[44:47], v[18:21], v[40:43], 0
	s_nop 7
	ds_write_b128 v51, v[44:47] offset:192
	v_mfma_f32_16x16x32_bf16 v[44:47], v[14:17], v[40:43], 0
	s_nop 7
	ds_write_b128 v51, v[44:47] offset:256
	v_mfma_f32_16x16x32_bf16 v[44:47], v[10:13], v[40:43], 0
	s_nop 7
	ds_write_b128 v51, v[44:47] offset:320
	v_mfma_f32_16x16x32_bf16 v[44:47], v[6:9], v[40:43], 0
	v_mfma_f32_16x16x32_bf16 v[40:43], v[2:5], v[40:43], 0
	s_nop 6
	ds_write_b128 v51, v[44:47] offset:384
	ds_write_b128 v51, v[40:43] offset:448
	s_waitcnt lgkmcnt(0)
	ds_read2_b64 v[40:43], v91 offset1:66
	v_pk_mul_f32 v[44:45], v[64:65], v[74:75]
	s_nop 0
	v_pk_fma_f32 v[46:47], v[62:63], v[74:75], v[44:45] op_sel:[0,0,1] op_sel_hi:[1,1,0] neg_lo:[0,0,1] neg_hi:[0,0,1]
	v_pk_fma_f32 v[44:45], v[62:63], v[74:75], v[44:45] op_sel:[0,0,1] op_sel_hi:[1,1,0]
	ds_read2_b64 v[74:77], v61 offset0:8 offset1:74
	v_mov_b32_e32 v47, v45
	s_waitcnt lgkmcnt(1)
; #define LAS __attribute__((address_space(3)))
; #define LDS_WAIT() asm volatile("s_waitcnt lgkmcnt(0)" ::: "memory")
; __device__ __forceinline__ u32x2 s5_load_u(const bf16_t* U, int t0, int g, int lane) { if (t0 > T - 16) t0 = T - 16; return *(const u32x2*)(U + (size_t)(t0 + (lane >> 2)) * D + g * 16 + (lane & 3) * 4); }
; __device__ __forceinline__ f32x4 s5_u_f32(const u32x2 w) { return (f32x4){bflo(w.x), bfhi(w.x), bflo(w.y), bfhi(w.y)}; }
; __device__ __forceinline__ void s5_bu_tile(const S5Item& L, const f32x4 ucur, LAS unsigned char* wlds, int lane) {
;     LAS float* ut = (LAS float*)(wlds + S5_OFF_U);
;     *(LAS f32x4*)(ut + (lane >> 2) * 16 + (lane & 3) * 4) = ucur;
;     LDS_WAIT(); __builtin_amdgcn_wave_barrier();
;     const LAS f32x4* up = (const LAS f32x4*)(ut + (lane & 15) * 16 + ((lane >> 4) & 1) * 8);
;     const f32x4 u0 = up[0], u1 = up[1];
;     u32x4 w; w.x = cvt_pk_bf16(u0[0], u0[1]); w.y = cvt_pk_bf16(u0[2], u0[3]); w.z = cvt_pk_bf16(u1[0], u1[1]); w.w = cvt_pk_bf16(u1[2], u1[3]);
;     const bf16x8 uf = __builtin_bit_cast(bf16x8, w);
; #pragma unroll
;     for (int f = 0; f < 8; ++f) {
;         f32x4 d = (f32x4){0.f, 0.f, 0.f, 0.f};
;         d = __builtin_amdgcn_mfma_f32_16x16x32_bf16(L.bf[f], uf, d, 0, 0, 0);
;         *(LAS f32x4*)(wlds + (lane & 15) * S5_BU_STRIDE + (16 * f + (lane >> 4) * 4) * 4) = d;
;     }
;     LDS_WAIT(); __builtin_amdgcn_wave_barrier();
; __device__ __forceinline__ void s5_scan1(LAS unsigned char* lds, const S5Params& P, const bf16_t* U, float* ES, int bid, int G) {
;     ...
;         for (int t0 = c * S5_L; t0 < (c + 1) * S5_L; t0 += 16) {
;             const f32x4 ucur = s5_u_f32(uq0);
;             uq0 = uq1; uq1 = uq2; uq2 = uq3; uq3 = s5_load_u(U, t0 + 64, g, lane);
;             s5_bu_tile(L, ucur, wlds, lane);
; #pragma unroll
;             for (int i = 0; i < 16; ++i) { const f32x2 bu = *(const LAS f32x2*)(wlds + i * S5_BU_STRIDE + lane * 8);
;                 const float nre = L.abr * sre - L.abi * sim + bu[0], nim = L.abr * sim + L.abi * sre + bu[1]; sre = nre; sim = nim; }
	v_pk_add_f32 v[40:41], v[46:47], v[40:41]
	s_nop 0
	v_pk_mul_f32 v[44:45], v[64:65], v[40:41]
	s_nop 0
	v_pk_fma_f32 v[48:49], v[62:63], v[40:41], v[44:45] op_sel:[0,0,1] op_sel_hi:[1,1,0] neg_lo:[0,0,1] neg_hi:[0,0,1]
	v_pk_fma_f32 v[40:41], v[62:63], v[40:41], v[44:45] op_sel:[0,0,1] op_sel_hi:[1,1,0]
	ds_read2_b64 v[44:47], v91 offset0:132 offset1:198
	v_mov_b32_e32 v49, v41
	v_pk_add_f32 v[40:41], v[42:43], v[48:49]
	s_nop 0
	v_pk_mul_f32 v[42:43], v[64:65], v[40:41]
	s_nop 0
	v_pk_fma_f32 v[48:49], v[62:63], v[40:41], v[42:43] op_sel:[0,0,1] op_sel_hi:[1,1,0]
	v_pk_fma_f32 v[40:41], v[62:63], v[40:41], v[42:43] op_sel:[0,0,1] op_sel_hi:[1,1,0] neg_lo:[0,0,1] neg_hi:[0,0,1]
	s_nop 0
	v_mov_b32_e32 v41, v49
	s_waitcnt lgkmcnt(0)
	v_pk_add_f32 v[40:41], v[44:45], v[40:41]
	s_nop 0
	v_pk_mul_f32 v[42:43], v[64:65], v[40:41]
	s_nop 0
	v_pk_fma_f32 v[44:45], v[62:63], v[40:41], v[42:43] op_sel:[0,0,1] op_sel_hi:[1,1,0]
	v_pk_fma_f32 v[40:41], v[62:63], v[40:41], v[42:43] op_sel:[0,0,1] op_sel_hi:[1,1,0] neg_lo:[0,0,1] neg_hi:[0,0,1]
	s_nop 0
	v_mov_b32_e32 v41, v45
	v_pk_add_f32 v[40:41], v[46:47], v[40:41]
	s_nop 0
	v_pk_mul_f32 v[42:43], v[64:65], v[40:41]
	s_nop 0
	v_pk_fma_f32 v[44:45], v[62:63], v[40:41], v[42:43] op_sel:[0,0,1] op_sel_hi:[1,1,0]
	v_pk_fma_f32 v[40:41], v[62:63], v[40:41], v[42:43] op_sel:[0,0,1] op_sel_hi:[1,1,0] neg_lo:[0,0,1] neg_hi:[0,0,1]
	s_nop 0
	v_mov_b32_e32 v41, v45
	v_pk_add_f32 v[40:41], v[74:75], v[40:41]
	s_nop 0
	v_mul_f32_e32 v42, v37, v41
	v_pk_fma_f32 v[48:49], v[36:37], v[40:41], v[42:43] op_sel_hi:[1,1,0] neg_lo:[0,0,1] neg_hi:[0,0,1]
	v_mul_f32_e32 v42, v30, v40
	v_pk_fma_f32 v[74:75], v[30:31], v[40:41], v[42:43] op_sel_hi:[1,1,0]
	ds_read2_b64 v[40:43], v61 offset0:140 offset1:206
	v_mov_b32_e32 v49, v75
	v_pk_add_f32 v[48:49], v[76:77], v[48:49]
	v_add_u32_e32 v61, 0x1000, v91
	v_pk_mul_f32 v[74:75], v[64:65], v[48:49]
	ds_read2_b64 v[44:47], v61 offset0:16 offset1:82
	v_pk_fma_f32 v[76:77], v[62:63], v[48:49], v[74:75] op_sel:[0,0,1] op_sel_hi:[1,1,0] neg_lo:[0,0,1] neg_hi:[0,0,1]
	v_pk_fma_f32 v[48:49], v[62:63], v[48:49], v[74:75] op_sel:[0,0,1] op_sel_hi:[1,1,0]
	s_nop 0
	v_mov_b32_e32 v77, v49
	s_waitcnt lgkmcnt(1)
	v_pk_add_f32 v[40:41], v[40:41], v[76:77]
	s_nop 0
	v_pk_mul_f32 v[48:49], v[64:65], v[40:41]
	s_nop 0
	v_pk_fma_f32 v[74:75], v[62:63], v[40:41], v[48:49] op_sel:[0,0,1] op_sel_hi:[1,1,0] neg_lo:[0,0,1] neg_hi:[0,0,1]
	v_pk_fma_f32 v[40:41], v[62:63], v[40:41], v[48:49] op_sel:[0,0,1] op_sel_hi:[1,1,0]
	s_nop 0
	v_mov_b32_e32 v75, v41
	v_pk_add_f32 v[40:41], v[42:43], v[74:75]
	s_nop 0
	v_pk_mul_f32 v[42:43], v[64:65], v[40:41]
	s_nop 0
	v_pk_fma_f32 v[48:49], v[62:63], v[40:41], v[42:43] op_sel:[0,0,1] op_sel_hi:[1,1,0] neg_lo:[0,0,1] neg_hi:[0,0,1]
	v_pk_fma_f32 v[40:41], v[62:63], v[40:41], v[42:43] op_sel:[0,0,1] op_sel_hi:[1,1,0]
	s_nop 0
	v_mov_b32_e32 v49, v41
	s_waitcnt lgkmcnt(0)
	v_pk_add_f32 v[44:45], v[44:45], v[48:49]
	ds_read2_b64 v[40:43], v61 offset0:148 offset1:214
	v_pk_mul_f32 v[48:49], v[64:65], v[44:45]
	v_add_u32_e32 v61, 0x1800, v91
	v_pk_fma_f32 v[92:93], v[62:63], v[44:45], v[48:49] op_sel:[0,0,1] op_sel_hi:[1,1,0] neg_lo:[0,0,1] neg_hi:[0,0,1]
	v_pk_fma_f32 v[44:45], v[62:63], v[44:45], v[48:49] op_sel:[0,0,1] op_sel_hi:[1,1,0]
	ds_read2_b64 v[74:77], v61 offset0:24 offset1:90
	v_mov_b32_e32 v93, v45
	v_pk_add_f32 v[44:45], v[46:47], v[92:93]
	s_nop 0
	v_pk_mul_f32 v[46:47], v[64:65], v[44:45]
	s_nop 0
	v_pk_fma_f32 v[48:49], v[62:63], v[44:45], v[46:47] op_sel:[0,0,1] op_sel_hi:[1,1,0] neg_lo:[0,0,1] neg_hi:[0,0,1]
	v_pk_fma_f32 v[44:45], v[62:63], v[44:45], v[46:47] op_sel:[0,0,1] op_sel_hi:[1,1,0]
	s_nop 0
	v_mov_b32_e32 v49, v45
	s_waitcnt lgkmcnt(1)
	v_pk_add_f32 v[40:41], v[40:41], v[48:49]
	s_nop 0
	v_pk_mul_f32 v[44:45], v[64:65], v[40:41]
	s_nop 0
	v_pk_fma_f32 v[46:47], v[62:63], v[40:41], v[44:45] op_sel:[0,0,1] op_sel_hi:[1,1,0] neg_lo:[0,0,1] neg_hi:[0,0,1]
	v_pk_fma_f32 v[40:41], v[62:63], v[40:41], v[44:45] op_sel:[0,0,1] op_sel_hi:[1,1,0]
	s_nop 0
	v_mov_b32_e32 v47, v41
	v_pk_add_f32 v[40:41], v[42:43], v[46:47]
	s_nop 0
	v_pk_mul_f32 v[42:43], v[64:65], v[40:41]
	s_nop 0
	v_pk_fma_f32 v[44:45], v[62:63], v[40:41], v[42:43] op_sel:[0,0,1] op_sel_hi:[1,1,0] neg_lo:[0,0,1] neg_hi:[0,0,1]
	v_pk_fma_f32 v[40:41], v[62:63], v[40:41], v[42:43] op_sel:[0,0,1] op_sel_hi:[1,1,0]
	s_nop 0
	v_mov_b32_e32 v45, v41
	s_waitcnt lgkmcnt(0)
	v_pk_add_f32 v[44:45], v[74:75], v[44:45]
	ds_read2_b64 v[40:43], v61 offset0:156 offset1:222
	v_pk_mul_f32 v[46:47], v[64:65], v[44:45]
	s_waitcnt lgkmcnt(0)
	s_nop 0
	v_pk_fma_f32 v[48:49], v[62:63], v[44:45], v[46:47] op_sel:[0,0,1] op_sel_hi:[1,1,0] neg_lo:[0,0,1] neg_hi:[0,0,1]
	v_pk_fma_f32 v[44:45], v[62:63], v[44:45], v[46:47] op_sel:[0,0,1] op_sel_hi:[1,1,0]
	s_nop 0
	v_mov_b32_e32 v49, v45
	v_pk_add_f32 v[44:45], v[76:77], v[48:49]
	v_pk_mul_f32 v[46:47], v[64:65], v[44:45]
	v_pk_fma_f32 v[48:49], v[62:63], v[44:45], v[46:47] op_sel:[0,0,1] op_sel_hi:[1,1,0] neg_lo:[0,0,1] neg_hi:[0,0,1]
	v_pk_fma_f32 v[44:45], v[62:63], v[44:45], v[46:47] op_sel:[0,0,1] op_sel_hi:[1,1,0]
	s_nop 0
	v_mov_b32_e32 v49, v45
	s_waitcnt lgkmcnt(0)
	v_pk_add_f32 v[40:41], v[40:41], v[48:49]
	s_nop 0
	v_pk_mul_f32 v[44:45], v[64:65], v[40:41]
	s_nop 0
	v_pk_fma_f32 v[46:47], v[62:63], v[40:41], v[44:45] op_sel:[0,0,1] op_sel_hi:[1,1,0] neg_lo:[0,0,1] neg_hi:[0,0,1]
	v_pk_fma_f32 v[40:41], v[62:63], v[40:41], v[44:45] op_sel:[0,0,1] op_sel_hi:[1,1,0]
	s_nop 0
	v_mov_b32_e32 v47, v41
	v_pk_add_f32 v[74:75], v[42:43], v[46:47]
	s_waitcnt vmcnt(3)
; #define LAS __attribute__((address_space(3)))
; #define LDS_WAIT() asm volatile("s_waitcnt lgkmcnt(0)" ::: "memory")
; __device__ __forceinline__ u32x2 s5_load_u(const bf16_t* U, int t0, int g, int lane) { if (t0 > T - 16) t0 = T - 16; return *(const u32x2*)(U + (size_t)(t0 + (lane >> 2)) * D + g * 16 + (lane & 3) * 4); }
; __device__ __forceinline__ f32x4 s5_u_f32(const u32x2 w) { return (f32x4){bflo(w.x), bfhi(w.x), bflo(w.y), bfhi(w.y)}; }
; __device__ __forceinline__ void s5_bu_tile(const S5Item& L, const f32x4 ucur, LAS unsigned char* wlds, int lane) {
;     LAS float* ut = (LAS float*)(wlds + S5_OFF_U);
;     *(LAS f32x4*)(ut + (lane >> 2) * 16 + (lane & 3) * 4) = ucur;
;     LDS_WAIT(); __builtin_amdgcn_wave_barrier();
;     const LAS f32x4* up = (const LAS f32x4*)(ut + (lane & 15) * 16 + ((lane >> 4) & 1) * 8);
;     const f32x4 u0 = up[0], u1 = up[1];
;     u32x4 w; w.x = cvt_pk_bf16(u0[0], u0[1]); w.y = cvt_pk_bf16(u0[2], u0[3]); w.z = cvt_pk_bf16(u1[0], u1[1]); w.w = cvt_pk_bf16(u1[2], u1[3]);
;     const bf16x8 uf = __builtin_bit_cast(bf16x8, w);
; #pragma unroll
;     for (int f = 0; f < 8; ++f) {
;         f32x4 d = (f32x4){0.f, 0.f, 0.f, 0.f};
;         d = __builtin_amdgcn_mfma_f32_16x16x32_bf16(L.bf[f], uf, d, 0, 0, 0);
;         *(LAS f32x4*)(wlds + (lane & 15) * S5_BU_STRIDE + (16 * f + (lane >> 4) * 4) * 4) = d;
;     }
;     LDS_WAIT(); __builtin_amdgcn_wave_barrier();
; __device__ __forceinline__ void s5_scan1(LAS unsigned char* lds, const S5Params& P, const bf16_t* U, float* ES, int bid, int G) {
;     ...
;         for (int t0 = c * S5_L; t0 < (c + 1) * S5_L; t0 += 16) {
;             const f32x4 ucur = s5_u_f32(uq0);
;             uq0 = uq1; uq1 = uq2; uq2 = uq3; uq3 = s5_load_u(U, t0 + 64, g, lane);
;             s5_bu_tile(L, ucur, wlds, lane);
; #pragma unroll
;             for (int i = 0; i < 16; ++i) { const f32x2 bu = *(const LAS f32x2*)(wlds + i * S5_BU_STRIDE + lane * 8);
;                 const float nre = L.abr * sre - L.abi * sim + bu[0], nim = L.abr * sim + L.abi * sre + bu[1]; sre = nre; sim = nim; }
	s_min_i32 s1, s8, 0x1fb0
	v_add_u32_e32 v44, s1, v88
	v_ashrrev_i32_e32 v45, 31, v44
	v_lshlrev_b32_e32 v40, 16, v100
	v_and_b32_e32 v41, 0xffff0000, v100
	v_lshlrev_b32_e32 v42, 16, v101
	v_and_b32_e32 v43, 0xffff0000, v101
	v_lshlrev_b64 v[44:45], 12, v[44:45]
	v_lshl_add_u64 v[44:45], v[66:67], 0, v[44:45]
	ds_write_b128 v89, v[40:43] offset:12800
	global_load_dwordx2 v[100:101], v[44:45], off
	s_waitcnt lgkmcnt(0)
	ds_read_b128 v[40:43], v90 offset:12800
	ds_read_b128 v[44:47], v90 offset:12816
	v_add_u32_e32 v61, 0x800, v91
	s_add_i32 s1, s8, 16
	s_cmp_ge_i32 s8, s0
	s_waitcnt lgkmcnt(1)
	v_cvt_pk_bf16_f32 v40, v40, v41
	v_cvt_pk_bf16_f32 v41, v42, v43
	s_waitcnt lgkmcnt(0)
	v_cvt_pk_bf16_f32 v42, v44, v45
	v_cvt_pk_bf16_f32 v43, v46, v47
	s_mov_b32 s8, s1
	s_nop 0
	v_mfma_f32_16x16x32_bf16 v[44:47], v[32:35], v[40:43], 0
	s_nop 7
	ds_write_b128 v51, v[44:47]
	v_mfma_f32_16x16x32_bf16 v[44:47], v[26:29], v[40:43], 0
	s_nop 7
	ds_write_b128 v51, v[44:47] offset:64
	v_mfma_f32_16x16x32_bf16 v[44:47], v[22:25], v[40:43], 0
	s_nop 7
	ds_write_b128 v51, v[44:47] offset:128
	v_mfma_f32_16x16x32_bf16 v[44:47], v[18:21], v[40:43], 0
	s_nop 7
	ds_write_b128 v51, v[44:47] offset:192
	v_mfma_f32_16x16x32_bf16 v[44:47], v[14:17], v[40:43], 0
	s_nop 7
	ds_write_b128 v51, v[44:47] offset:256
	v_mfma_f32_16x16x32_bf16 v[44:47], v[10:13], v[40:43], 0
	s_nop 7
	ds_write_b128 v51, v[44:47] offset:320
	v_mfma_f32_16x16x32_bf16 v[44:47], v[6:9], v[40:43], 0
	v_mfma_f32_16x16x32_bf16 v[40:43], v[2:5], v[40:43], 0
	s_nop 6
	ds_write_b128 v51, v[44:47] offset:384
	ds_write_b128 v51, v[40:43] offset:448
	s_waitcnt lgkmcnt(0)
	ds_read2_b64 v[40:43], v91 offset1:66
	v_pk_mul_f32 v[44:45], v[64:65], v[74:75]
	s_nop 0
	v_pk_fma_f32 v[46:47], v[62:63], v[74:75], v[44:45] op_sel:[0,0,1] op_sel_hi:[1,1,0] neg_lo:[0,0,1] neg_hi:[0,0,1]
	v_pk_fma_f32 v[44:45], v[62:63], v[74:75], v[44:45] op_sel:[0,0,1] op_sel_hi:[1,1,0]
	ds_read2_b64 v[74:77], v61 offset0:8 offset1:74
	v_mov_b32_e32 v47, v45
	s_waitcnt lgkmcnt(1)
	v_pk_add_f32 v[40:41], v[46:47], v[40:41]
	s_nop 0
	v_pk_mul_f32 v[44:45], v[64:65], v[40:41]
	s_nop 0
	v_pk_fma_f32 v[48:49], v[62:63], v[40:41], v[44:45] op_sel:[0,0,1] op_sel_hi:[1,1,0] neg_lo:[0,0,1] neg_hi:[0,0,1]
	v_pk_fma_f32 v[40:41], v[62:63], v[40:41], v[44:45] op_sel:[0,0,1] op_sel_hi:[1,1,0]
	ds_read2_b64 v[44:47], v91 offset0:132 offset1:198
	v_mov_b32_e32 v49, v41
	v_pk_add_f32 v[40:41], v[42:43], v[48:49]
	s_nop 0
	v_pk_mul_f32 v[42:43], v[64:65], v[40:41]
	s_nop 0
	v_pk_fma_f32 v[48:49], v[62:63], v[40:41], v[42:43] op_sel:[0,0,1] op_sel_hi:[1,1,0]
	v_pk_fma_f32 v[40:41], v[62:63], v[40:41], v[42:43] op_sel:[0,0,1] op_sel_hi:[1,1,0] neg_lo:[0,0,1] neg_hi:[0,0,1]
	s_nop 0
	v_mov_b32_e32 v41, v49
	s_waitcnt lgkmcnt(0)
	v_pk_add_f32 v[40:41], v[44:45], v[40:41]
	s_nop 0
	v_pk_mul_f32 v[42:43], v[64:65], v[40:41]
	s_nop 0
	v_pk_fma_f32 v[44:45], v[62:63], v[40:41], v[42:43] op_sel:[0,0,1] op_sel_hi:[1,1,0]
	v_pk_fma_f32 v[40:41], v[62:63], v[40:41], v[42:43] op_sel:[0,0,1] op_sel_hi:[1,1,0] neg_lo:[0,0,1] neg_hi:[0,0,1]
	s_nop 0
	v_mov_b32_e32 v41, v45
	v_pk_add_f32 v[40:41], v[46:47], v[40:41]
	s_nop 0
	v_pk_mul_f32 v[42:43], v[64:65], v[40:41]
	s_nop 0
	v_pk_fma_f32 v[44:45], v[62:63], v[40:41], v[42:43] op_sel:[0,0,1] op_sel_hi:[1,1,0]
	v_pk_fma_f32 v[40:41], v[62:63], v[40:41], v[42:43] op_sel:[0,0,1] op_sel_hi:[1,1,0] neg_lo:[0,0,1] neg_hi:[0,0,1]
	s_nop 0
	v_mov_b32_e32 v41, v45
	v_pk_add_f32 v[40:41], v[74:75], v[40:41]
	s_nop 0
	v_mul_f32_e32 v42, v37, v41
	v_pk_fma_f32 v[48:49], v[36:37], v[40:41], v[42:43] op_sel_hi:[1,1,0] neg_lo:[0,0,1] neg_hi:[0,0,1]
	v_mul_f32_e32 v42, v30, v40
	v_pk_fma_f32 v[74:75], v[30:31], v[40:41], v[42:43] op_sel_hi:[1,1,0]
	ds_read2_b64 v[40:43], v61 offset0:140 offset1:206
	v_mov_b32_e32 v49, v75
	v_pk_add_f32 v[48:49], v[76:77], v[48:49]
	v_add_u32_e32 v61, 0x1000, v91
	v_pk_mul_f32 v[74:75], v[64:65], v[48:49]
	ds_read2_b64 v[44:47], v61 offset0:16 offset1:82
	v_pk_fma_f32 v[76:77], v[62:63], v[48:49], v[74:75] op_sel:[0,0,1] op_sel_hi:[1,1,0] neg_lo:[0,0,1] neg_hi:[0,0,1]
	v_pk_fma_f32 v[48:49], v[62:63], v[48:49], v[74:75] op_sel:[0,0,1] op_sel_hi:[1,1,0]
	s_nop 0
	v_mov_b32_e32 v77, v49
	s_waitcnt lgkmcnt(1)
; #define LAS __attribute__((address_space(3)))
; #define LDS_WAIT() asm volatile("s_waitcnt lgkmcnt(0)" ::: "memory")
; __device__ __forceinline__ u32x2 s5_load_u(const bf16_t* U, int t0, int g, int lane) { if (t0 > T - 16) t0 = T - 16; return *(const u32x2*)(U + (size_t)(t0 + (lane >> 2)) * D + g * 16 + (lane & 3) * 4); }
; __device__ __forceinline__ f32x4 s5_u_f32(const u32x2 w) { return (f32x4){bflo(w.x), bfhi(w.x), bflo(w.y), bfhi(w.y)}; }
; __device__ __forceinline__ void s5_scan1(LAS unsigned char* lds, const S5Params& P, const bf16_t* U, float* ES, int bid, int G) {
;     ...
;     for (int item = gw; item < 128 * S5_NC; item += ngw) {
;         const int g = item & 127, c = item >> 7;
;         S5Item L; s5_item_setup(P, g, lane, wlds, L);
;         float sre = 0.f, sim = 0.f;
;         u32x2 uq0 = s5_load_u(U, c * S5_L, g, lane), uq1 = s5_load_u(U, c * S5_L + 16, g, lane), uq2 = s5_load_u(U, c * S5_L + 32, g, lane), uq3 = s5_load_u(U, c * S5_L + 48, g, lane);
;         for (int t0 = c * S5_L; t0 < (c + 1) * S5_L; t0 += 16) {
;             const f32x4 ucur = s5_u_f32(uq0);
;             uq0 = uq1; uq1 = uq2; uq2 = uq3; uq3 = s5_load_u(U, t0 + 64, g, lane);
;             s5_bu_tile(L, ucur, wlds, lane);
; #pragma unroll
;             for (int i = 0; i < 16; ++i) { const f32x2 bu = *(const LAS f32x2*)(wlds + i * S5_BU_STRIDE + lane * 8);
;                 const float nre = L.abr * sre - L.abi * sim + bu[0], nim = L.abr * sim + L.abi * sre + bu[1]; sre = nre; sim = nim; }
;             LDS_WAIT(); __builtin_amdgcn_wave_barrier();
;         }
;         *(f32x2*)(ES + ((size_t)(g * S5_NC + c) * 64 + lane) * 2) = (f32x2){sre, sim};
;     }
	v_pk_add_f32 v[40:41], v[40:41], v[76:77]
	s_nop 0
	v_pk_mul_f32 v[48:49], v[64:65], v[40:41]
	s_nop 0
	v_pk_fma_f32 v[74:75], v[62:63], v[40:41], v[48:49] op_sel:[0,0,1] op_sel_hi:[1,1,0] neg_lo:[0,0,1] neg_hi:[0,0,1]
	v_pk_fma_f32 v[40:41], v[62:63], v[40:41], v[48:49] op_sel:[0,0,1] op_sel_hi:[1,1,0]
	s_nop 0
	v_mov_b32_e32 v75, v41
	v_pk_add_f32 v[40:41], v[42:43], v[74:75]
	s_nop 0
	v_pk_mul_f32 v[42:43], v[64:65], v[40:41]
	s_nop 0
	v_pk_fma_f32 v[48:49], v[62:63], v[40:41], v[42:43] op_sel:[0,0,1] op_sel_hi:[1,1,0] neg_lo:[0,0,1] neg_hi:[0,0,1]
	v_pk_fma_f32 v[40:41], v[62:63], v[40:41], v[42:43] op_sel:[0,0,1] op_sel_hi:[1,1,0]
	s_nop 0
	v_mov_b32_e32 v49, v41
	s_waitcnt lgkmcnt(0)
	v_pk_add_f32 v[44:45], v[44:45], v[48:49]
	ds_read2_b64 v[40:43], v61 offset0:148 offset1:214
	v_pk_mul_f32 v[48:49], v[64:65], v[44:45]
	v_add_u32_e32 v61, 0x1800, v91
	v_pk_fma_f32 v[92:93], v[62:63], v[44:45], v[48:49] op_sel:[0,0,1] op_sel_hi:[1,1,0] neg_lo:[0,0,1] neg_hi:[0,0,1]
	v_pk_fma_f32 v[44:45], v[62:63], v[44:45], v[48:49] op_sel:[0,0,1] op_sel_hi:[1,1,0]
	ds_read2_b64 v[74:77], v61 offset0:24 offset1:90
	v_mov_b32_e32 v93, v45
	v_pk_add_f32 v[44:45], v[46:47], v[92:93]
	s_nop 0
	v_pk_mul_f32 v[46:47], v[64:65], v[44:45]
	s_nop 0
	v_pk_fma_f32 v[48:49], v[62:63], v[44:45], v[46:47] op_sel:[0,0,1] op_sel_hi:[1,1,0] neg_lo:[0,0,1] neg_hi:[0,0,1]
	v_pk_fma_f32 v[44:45], v[62:63], v[44:45], v[46:47] op_sel:[0,0,1] op_sel_hi:[1,1,0]
	s_nop 0
	v_mov_b32_e32 v49, v45
	s_waitcnt lgkmcnt(1)
	v_pk_add_f32 v[40:41], v[40:41], v[48:49]
	s_nop 0
	v_pk_mul_f32 v[44:45], v[64:65], v[40:41]
	s_nop 0
	v_pk_fma_f32 v[46:47], v[62:63], v[40:41], v[44:45] op_sel:[0,0,1] op_sel_hi:[1,1,0] neg_lo:[0,0,1] neg_hi:[0,0,1]
	v_pk_fma_f32 v[40:41], v[62:63], v[40:41], v[44:45] op_sel:[0,0,1] op_sel_hi:[1,1,0]
	s_nop 0
	v_mov_b32_e32 v47, v41
	v_pk_add_f32 v[40:41], v[42:43], v[46:47]
	s_nop 0
	v_pk_mul_f32 v[42:43], v[64:65], v[40:41]
	s_nop 0
	v_pk_fma_f32 v[44:45], v[62:63], v[40:41], v[42:43] op_sel:[0,0,1] op_sel_hi:[1,1,0] neg_lo:[0,0,1] neg_hi:[0,0,1]
	v_pk_fma_f32 v[40:41], v[62:63], v[40:41], v[42:43] op_sel:[0,0,1] op_sel_hi:[1,1,0]
	s_nop 0
	v_mov_b32_e32 v45, v41
	s_waitcnt lgkmcnt(0)
	v_pk_add_f32 v[44:45], v[74:75], v[44:45]
	ds_read2_b64 v[40:43], v61 offset0:156 offset1:222
	v_pk_mul_f32 v[46:47], v[64:65], v[44:45]
	s_waitcnt lgkmcnt(0)
	s_nop 0
	v_pk_fma_f32 v[48:49], v[62:63], v[44:45], v[46:47] op_sel:[0,0,1] op_sel_hi:[1,1,0] neg_lo:[0,0,1] neg_hi:[0,0,1]
	v_pk_fma_f32 v[44:45], v[62:63], v[44:45], v[46:47] op_sel:[0,0,1] op_sel_hi:[1,1,0]
	s_nop 0
	v_mov_b32_e32 v49, v45
	v_pk_add_f32 v[44:45], v[76:77], v[48:49]
	v_pk_mul_f32 v[46:47], v[64:65], v[44:45]
	v_pk_fma_f32 v[48:49], v[62:63], v[44:45], v[46:47] op_sel:[0,0,1] op_sel_hi:[1,1,0] neg_lo:[0,0,1] neg_hi:[0,0,1]
	v_pk_fma_f32 v[44:45], v[62:63], v[44:45], v[46:47] op_sel:[0,0,1] op_sel_hi:[1,1,0]
	s_nop 0
	v_mov_b32_e32 v49, v45
	s_waitcnt lgkmcnt(0)
	v_pk_add_f32 v[40:41], v[40:41], v[48:49]
	s_nop 0
	v_pk_mul_f32 v[44:45], v[64:65], v[40:41]
	s_nop 0
	v_pk_fma_f32 v[46:47], v[62:63], v[40:41], v[44:45] op_sel:[0,0,1] op_sel_hi:[1,1,0] neg_lo:[0,0,1] neg_hi:[0,0,1]
	v_pk_fma_f32 v[40:41], v[62:63], v[40:41], v[44:45] op_sel:[0,0,1] op_sel_hi:[1,1,0]
	s_nop 0
	v_mov_b32_e32 v47, v41
	v_pk_add_f32 v[74:75], v[42:43], v[46:47]
	s_cbranch_scc0 .LBB0_1179
	s_add_i32 s0, s42, s10
	s_ashr_i32 s1, s0, 31
	s_lshl_b64 s[0:1], s[0:1], 9
	s_add_i32 s44, s44, s82
	v_lshl_add_u64 v[2:3], v[54:55], 0, s[0:1]
	s_cmpk_gt_i32 s44, 0xfff
	global_store_dwordx2 v[2:3], v[74:75], off
	s_cbranch_scc0 .LBB0_1170
